# out phase: dropped the unit-header vmcnt(0) drain before the K-loop (it only waited for the previous epilogue's store acks)
# speedup vs baseline: 1.0247x; 1.0039x over previous
; #define PG8_STAGE(bufoff, gbase, voff) do { _Pragma("unroll") for (int _i = 0; _i < 2; ++_i) \
;         __builtin_amdgcn_global_load_lds((const unsigned*)((const char*)(gbase) + (voff)[_i]), (PG8_LAS unsigned*)(lds + (bufoff) + ldsw + _i * 8192), 16, 0, 0); } while (0)
; #define PG8_LDA(dst, b, h) do { _Pragma("unroll") for (int m = 0; m < 4; ++m) _Pragma("unroll") for (int k = 0; k < 2; ++k) dst[m][k] = *(const PG8_LAS bf16x8*)(lds + PG8_SA(b, h) + aoff + m * 2048 + k * 1024); } while (0)
; template <class Epi, class Sched>
; __device__ __forceinline__ void gemm_phase(PG8_LAS unsigned char* lds, const Gemm g, const Sched& S, const Epi& E) {
;     ...
;     for (;;) {
;         const bool has_next = S.next(ui + 1, nxt);
;         const char* nA = has_next ? (const char*)g.A + (size_t)nxt.pm * tstep : cA; const char* nB = has_next ? (const char*)g.Bt + (size_t)nxt.pn * tstep : cB;
;         for (int t = 0; t < nt; t += 2) {
;             const bool last = (t == nt - 2);
;             const char* a1 = cA + (size_t)(t + 1) * kstep;
;             const char* a2 = last ? nA : cA + (size_t)(t + 2) * kstep; const char* b2 = last ? nB : cB + (size_t)(t + 2) * kstep;
;             const char* a3 = a2 + kstep; const char* b3 = b2 + kstep;
;             if (last && has_next) S.a_ready(nxt);
;             if constexpr (Epi::MIDK) { if (t == nt / 2) E.mid(acc, cur, wr, wc, fr, fq); }
;             PG8_LDB(B0, 0, 0); PG8_SCHED; PG8_LDA(At, 0, 0); PG8_STAGE(PG8_SA(1, 1), a1 + hstep, voffA);
;             PG8_WAIT_L(8); PG8_BAR; PG8_WAIT_L(0); PG8_MMA(0, 0, At, B0); PG8_BAR; PG8_SCHED;
;             PG8_LDB(B1, 0, 1); PG8_STAGE(PG8_SB(0, 0), b2, voffB);
;             PG8_BAR; PG8_WAIT_L(0); PG8_MMA(0, 1, At, B1); PG8_BAR;
;             PG8_LDA(At, 0, 1); PG8_STAGE(PG8_SA(0, 0), a2, voffA);
;             PG8_BAR; PG8_WAIT_L(0); PG8_MMA(1, 0, At, B0); PG8_BAR; PG8_SCHED;
;             PG8_STAGE(PG8_SB(0, 1), b2 + hstep, voffB);
;             PG8_WAIT_V(6); PG8_BAR; PG8_MMA(1, 1, At, B1); PG8_BAR;
;     ...
;         if (!has_next) break;
; #pragma unroll
;         for (int a = 0; a < 2; ++a)
; #pragma unroll
;             for (int b = 0; b < 2; ++b)
; #pragma unroll
;                 for (int m = 0; m < 4; ++m)
; #pragma unroll
;                     for (int n = 0; n < 2; ++n) acc[a][b][m][n] = (f32x4){0.f, 0.f, 0.f, 0.f};
;         cur = nxt; cA = nA; cB = nB; ++ui;
.LBB0_2753:
	s_ashr_i32 s5, s4, 31
	v_cmp_lt_i64_e32 vcc, s[6:7], v[160:161]
	s_lshl_b64 s[6:7], s[4:5], 19
	v_readlane_b32 s8, v250, 30
	v_readlane_b32 s9, v250, 31
	s_add_u32 s6, s8, s6
	s_addc_u32 s7, s9, s7
	s_and_b64 s[8:9], vcc, exec
	s_cselect_b32 s5, s7, s13
	s_cselect_b32 s31, s6, s12
	s_ashr_i32 s3, s2, 31
	s_lshl_b64 s[8:9], s[2:3], 19
	v_readlane_b32 s3, v250, 46
	s_add_u32 s8, s3, s8
	v_readlane_b32 s3, v250, 47
	s_addc_u32 s9, s3, s9
	s_and_b64 s[16:17], vcc, exec
	s_cselect_b32 s3, s9, s15
	s_cselect_b32 s33, s8, s14
	s_add_u32 s12, s12, 0x40080
	s_addc_u32 s13, s13, 0
	s_add_u32 s34, s14, 0x100
	v_mov_b32_e32 v0, 0
	s_addc_u32 s35, s15, 0
	s_mov_b32 s36, -2
	v_mov_b32_e32 v1, v0
	v_mov_b32_e32 v2, v0
	v_mov_b32_e32 v3, v0
	v_mov_b32_e32 v4, v0
	v_mov_b32_e32 v5, v0
	v_mov_b32_e32 v6, v0
	v_mov_b32_e32 v7, v0
	v_mov_b32_e32 v22, v0
	v_mov_b32_e32 v23, v0
	v_mov_b32_e32 v24, v0
	v_mov_b32_e32 v25, v0
	v_mov_b32_e32 v26, v0
	v_mov_b32_e32 v27, v0
	v_mov_b32_e32 v28, v0
	v_mov_b32_e32 v29, v0
	v_mov_b32_e32 v38, v0
	v_mov_b32_e32 v39, v0
	v_mov_b32_e32 v40, v0
	v_mov_b32_e32 v41, v0
	v_mov_b32_e32 v42, v0
	v_mov_b32_e32 v43, v0
	v_mov_b32_e32 v44, v0
	v_mov_b32_e32 v45, v0
	v_mov_b32_e32 v54, v0
	v_mov_b32_e32 v55, v0
	v_mov_b32_e32 v56, v0
	v_mov_b32_e32 v57, v0
	v_mov_b32_e32 v58, v0
	v_mov_b32_e32 v59, v0
	v_mov_b32_e32 v60, v0
	v_mov_b32_e32 v61, v0
	v_mov_b32_e32 v8, v0
	v_mov_b32_e32 v9, v0
	v_mov_b32_e32 v10, v0
	v_mov_b32_e32 v11, v0
	v_mov_b32_e32 v12, v0
	v_mov_b32_e32 v13, v0
	v_mov_b32_e32 v14, v0
	v_mov_b32_e32 v15, v0
	v_mov_b32_e32 v30, v0
	v_mov_b32_e32 v31, v0
	v_mov_b32_e32 v32, v0
	v_mov_b32_e32 v33, v0
	v_mov_b32_e32 v34, v0
	v_mov_b32_e32 v35, v0
	v_mov_b32_e32 v36, v0
	v_mov_b32_e32 v37, v0
	v_mov_b32_e32 v46, v0
	v_mov_b32_e32 v47, v0
	v_mov_b32_e32 v48, v0
	v_mov_b32_e32 v49, v0
	v_mov_b32_e32 v50, v0
	v_mov_b32_e32 v51, v0
	v_mov_b32_e32 v52, v0
	v_mov_b32_e32 v53, v0
	v_mov_b32_e32 v62, v0
	v_mov_b32_e32 v63, v0
	v_mov_b32_e32 v64, v0
	v_mov_b32_e32 v65, v0
	v_mov_b32_e32 v66, v0
	v_mov_b32_e32 v67, v0
	v_mov_b32_e32 v68, v0
	v_mov_b32_e32 v69, v0
	v_mov_b32_e32 v70, v0
	v_mov_b32_e32 v71, v0
	v_mov_b32_e32 v72, v0
	v_mov_b32_e32 v73, v0
	v_mov_b32_e32 v74, v0
	v_mov_b32_e32 v75, v0
	v_mov_b32_e32 v76, v0
	v_mov_b32_e32 v77, v0
	v_mov_b32_e32 v86, v0
	v_mov_b32_e32 v87, v0
	v_mov_b32_e32 v88, v0
	v_mov_b32_e32 v89, v0
	v_mov_b32_e32 v90, v0
	v_mov_b32_e32 v91, v0
	v_mov_b32_e32 v92, v0
	v_mov_b32_e32 v93, v0
	v_mov_b32_e32 v102, v0
	v_mov_b32_e32 v103, v0
	v_mov_b32_e32 v104, v0
	v_mov_b32_e32 v105, v0
	v_mov_b32_e32 v106, v0
	v_mov_b32_e32 v107, v0
	v_mov_b32_e32 v108, v0
	v_mov_b32_e32 v109, v0
	v_mov_b32_e32 v118, v0
	v_mov_b32_e32 v119, v0
	v_mov_b32_e32 v120, v0
	v_mov_b32_e32 v121, v0
	v_mov_b32_e32 v122, v0
	v_mov_b32_e32 v123, v0
	v_mov_b32_e32 v124, v0
	v_mov_b32_e32 v125, v0
	v_mov_b32_e32 v78, v0
	v_mov_b32_e32 v79, v0
	v_mov_b32_e32 v80, v0
	v_mov_b32_e32 v81, v0
	v_mov_b32_e32 v82, v0
	v_mov_b32_e32 v83, v0
	v_mov_b32_e32 v84, v0
	v_mov_b32_e32 v85, v0
	v_mov_b32_e32 v94, v0
	v_mov_b32_e32 v95, v0
	v_mov_b32_e32 v96, v0
	v_mov_b32_e32 v97, v0
	v_mov_b32_e32 v98, v0
	v_mov_b32_e32 v99, v0
	v_mov_b32_e32 v100, v0
	v_mov_b32_e32 v101, v0
	v_mov_b32_e32 v110, v0
	v_mov_b32_e32 v111, v0
	v_mov_b32_e32 v112, v0
	v_mov_b32_e32 v113, v0
	v_mov_b32_e32 v114, v0
	v_mov_b32_e32 v115, v0
	v_mov_b32_e32 v116, v0
	v_mov_b32_e32 v117, v0
	v_mov_b32_e32 v126, v0
	v_mov_b32_e32 v127, v0
	v_mov_b32_e32 v128, v0
	v_mov_b32_e32 v129, v0
	v_mov_b32_e32 v130, v0
	v_mov_b32_e32 v131, v0
	v_mov_b32_e32 v132, v0
	v_mov_b32_e32 v133, v0
	s_mov_b64 s[42:43], 0x80
.LBB0_2754:
	s_add_u32 s14, s12, 0xfffc0080
	s_addc_u32 s15, s13, -1
	s_add_i32 s37, 0, 0x10000
	v_add_u32_e32 v140, s37, v142
	ds_read_b128 v[144:147], v140
	ds_read_b128 v[148:151], v140 offset:1024
	ds_read_b128 v[162:165], v140 offset:2048
	ds_read_b128 v[166:169], v140 offset:3072
	s_cmp_eq_u32 s36, 12
	s_cselect_b32 s17, s5, s15
	s_cselect_b32 s16, s31, s14
	s_cselect_b32 s15, s3, s35
	s_cselect_b32 s14, s33, s34
	v_lshl_add_u64 v[140:141], s[12:13], 0, v[136:137]
	s_add_i32 m0, s23, 0xc000
	ds_read_b128 v[170:173], v143
	ds_read_b128 v[174:177], v143 offset:1024
	ds_read_b128 v[178:181], v143 offset:2048
	ds_read_b128 v[188:191], v143 offset:3072
	ds_read_b128 v[192:195], v143 offset:4096
	ds_read_b128 v[196:199], v143 offset:5120
	ds_read_b128 v[200:203], v143 offset:6144
	ds_read_b128 v[204:207], v143 offset:7168
	global_load_lds_dwordx4 v[140:141], off
	v_lshl_add_u64 v[140:141], s[12:13], 0, v[138:139]
	s_add_i32 m0, s23, 0xe000
	s_nop 0
	global_load_lds_dwordx4 v[140:141], off
	s_waitcnt lgkmcnt(8)
	s_barrier
	s_waitcnt lgkmcnt(0)
	s_setprio 1
	s_waitcnt lgkmcnt(0)
	v_mfma_f32_16x16x32_bf16 v[130:133], v[144:147], v[170:173], v[130:133]
	v_mfma_f32_16x16x32_bf16 v[126:129], v[162:165], v[170:173], v[126:129]
	v_mfma_f32_16x16x32_bf16 v[114:117], v[144:147], v[178:181], v[114:117]
	v_mfma_f32_16x16x32_bf16 v[110:113], v[162:165], v[178:181], v[110:113]
	v_mfma_f32_16x16x32_bf16 v[98:101], v[144:147], v[192:195], v[98:101]
	v_mfma_f32_16x16x32_bf16 v[94:97], v[162:165], v[192:195], v[94:97]
	v_mfma_f32_16x16x32_bf16 v[82:85], v[144:147], v[200:203], v[82:85]
	v_mfma_f32_16x16x32_bf16 v[78:81], v[162:165], v[200:203], v[78:81]
	v_mfma_f32_16x16x32_bf16 v[130:133], v[148:151], v[174:177], v[130:133]
	v_mfma_f32_16x16x32_bf16 v[126:129], v[166:169], v[174:177], v[126:129]
	v_mfma_f32_16x16x32_bf16 v[114:117], v[148:151], v[188:191], v[114:117]
	v_mfma_f32_16x16x32_bf16 v[110:113], v[166:169], v[188:191], v[110:113]
	v_mfma_f32_16x16x32_bf16 v[98:101], v[148:151], v[196:199], v[98:101]
	v_mfma_f32_16x16x32_bf16 v[94:97], v[166:169], v[196:199], v[94:97]
	v_mfma_f32_16x16x32_bf16 v[82:85], v[148:151], v[204:207], v[82:85]
	v_mfma_f32_16x16x32_bf16 v[78:81], v[166:169], v[204:207], v[78:81]
	s_setprio 0
	s_barrier
; #define PG8_STAGE(bufoff, gbase, voff) do { _Pragma("unroll") for (int _i = 0; _i < 2; ++_i) \
;         __builtin_amdgcn_global_load_lds((const unsigned*)((const char*)(gbase) + (voff)[_i]), (PG8_LAS unsigned*)(lds + (bufoff) + ldsw + _i * 8192), 16, 0, 0); } while (0)
; #define PG8_LDA(dst, b, h) do { _Pragma("unroll") for (int m = 0; m < 4; ++m) _Pragma("unroll") for (int k = 0; k < 2; ++k) dst[m][k] = *(const PG8_LAS bf16x8*)(lds + PG8_SA(b, h) + aoff + m * 2048 + k * 1024); } while (0)
; #define PG8_LDB(dst, b, h) do { _Pragma("unroll") for (int n = 0; n < 2; ++n) _Pragma("unroll") for (int k = 0; k < 2; ++k) dst[n][k] = *(const PG8_LAS bf16x8*)(lds + PG8_SB(b, h) + boff + n * 2048 + k * 1024); } while (0)
; #define PG8_MMA(ai, bj, At, Bt) do { __builtin_amdgcn_s_setprio(1); _Pragma("unroll") for (int m = 0; m < 4; ++m) _Pragma("unroll") for (int n = 0; n < 2; ++n) _Pragma("unroll") for (int k = 0; k < 2; ++k) \
;         acc[ai][bj][m][n] = __builtin_amdgcn_mfma_f32_16x16x32_bf16(Bt[n][k], At[m][k], acc[ai][bj][m][n], 0, 0, 0); __builtin_amdgcn_s_setprio(0); } while (0)
; template <class Epi, class Sched>
; __device__ __forceinline__ void gemm_phase(PG8_LAS unsigned char* lds, const Gemm g, const Sched& S, const Epi& E) {
;     ...
;             PG8_LDB(B0, 0, 0); PG8_SCHED; PG8_LDA(At, 0, 0); PG8_STAGE(PG8_SA(1, 1), a1 + hstep, voffA);
;             PG8_WAIT_L(8); PG8_BAR; PG8_WAIT_L(0); PG8_MMA(0, 0, At, B0); PG8_BAR; PG8_SCHED;
;             PG8_LDB(B1, 0, 1); PG8_STAGE(PG8_SB(0, 0), b2, voffB);
;             PG8_BAR; PG8_WAIT_L(0); PG8_MMA(0, 1, At, B1); PG8_BAR;
;             PG8_LDA(At, 0, 1); PG8_STAGE(PG8_SA(0, 0), a2, voffA);
;             PG8_BAR; PG8_WAIT_L(0); PG8_MMA(1, 0, At, B0); PG8_BAR; PG8_SCHED;
;             PG8_STAGE(PG8_SB(0, 1), b2 + hstep, voffB);
;             PG8_WAIT_V(6); PG8_BAR; PG8_MMA(1, 1, At, B1); PG8_BAR;
;             PG8_LDB(B0, 1, 0); PG8_SCHED; PG8_LDA(At, 1, 0); PG8_STAGE(PG8_SA(0, 1), a2 + hstep, voffA);
;             PG8_WAIT_L(8); PG8_BAR; PG8_WAIT_L(0); PG8_MMA(0, 0, At, B0); PG8_BAR; PG8_SCHED;
;             PG8_LDB(B1, 1, 1); PG8_STAGE(PG8_SB(1, 0), b3, voffB);
;             PG8_BAR; PG8_WAIT_L(0); PG8_MMA(0, 1, At, B1); PG8_BAR;
;             PG8_LDA(At, 1, 1); PG8_STAGE(PG8_SA(1, 0), a3, voffA);
;             PG8_BAR; PG8_WAIT_L(0); PG8_MMA(1, 0, At, B0); PG8_BAR; PG8_SCHED;
	s_add_i32 s40, 0, 0x14000
	v_add_u32_e32 v140, s40, v142
	s_add_i32 s37, s37, s21
	ds_read_b128 v[208:211], v140
	ds_read_b128 v[212:215], v140 offset:1024
	ds_read_b128 v[216:219], v140 offset:2048
	ds_read_b128 v[220:223], v140 offset:3072
	v_lshl_add_u64 v[140:141], s[14:15], 0, v[134:135]
	s_mov_b32 m0, s37
	v_lshl_add_u64 v[154:155], s[14:15], 0, v[18:19]
	global_load_lds_dwordx4 v[140:141], off
	s_add_i32 m0, s37, 0x2000
	s_nop 0
	global_load_lds_dwordx4 v[154:155], off
	s_barrier
	s_waitcnt lgkmcnt(0)
	s_setprio 1
	s_waitcnt lgkmcnt(0)
	v_mfma_f32_16x16x32_bf16 v[122:125], v[208:211], v[170:173], v[122:125]
	v_mfma_f32_16x16x32_bf16 v[118:121], v[216:219], v[170:173], v[118:121]
	v_mfma_f32_16x16x32_bf16 v[106:109], v[208:211], v[178:181], v[106:109]
	v_mfma_f32_16x16x32_bf16 v[102:105], v[216:219], v[178:181], v[102:105]
	v_mfma_f32_16x16x32_bf16 v[90:93], v[208:211], v[192:195], v[90:93]
	v_mfma_f32_16x16x32_bf16 v[86:89], v[216:219], v[192:195], v[86:89]
	v_mfma_f32_16x16x32_bf16 v[74:77], v[208:211], v[200:203], v[74:77]
	v_mfma_f32_16x16x32_bf16 v[70:73], v[216:219], v[200:203], v[70:73]
	v_mfma_f32_16x16x32_bf16 v[122:125], v[212:215], v[174:177], v[122:125]
	v_mfma_f32_16x16x32_bf16 v[118:121], v[220:223], v[174:177], v[118:121]
	v_mfma_f32_16x16x32_bf16 v[106:109], v[212:215], v[188:191], v[106:109]
	v_mfma_f32_16x16x32_bf16 v[102:105], v[220:223], v[188:191], v[102:105]
	v_mfma_f32_16x16x32_bf16 v[90:93], v[212:215], v[196:199], v[90:93]
	v_mfma_f32_16x16x32_bf16 v[86:89], v[220:223], v[196:199], v[86:89]
	v_mfma_f32_16x16x32_bf16 v[74:77], v[212:215], v[204:207], v[74:77]
	v_mfma_f32_16x16x32_bf16 v[70:73], v[220:223], v[204:207], v[70:73]
	s_setprio 0
	s_mov_b32 m0, s23
	v_lshl_add_u64 v[156:157], s[16:17], 0, v[134:135]
	s_barrier
	ds_read_b128 v[170:173], v143 offset:16384
	ds_read_b128 v[174:177], v143 offset:17408
	ds_read_b128 v[178:181], v143 offset:18432
	ds_read_b128 v[188:191], v143 offset:19456
	ds_read_b128 v[192:195], v143 offset:20480
	ds_read_b128 v[196:199], v143 offset:21504
	ds_read_b128 v[200:203], v143 offset:22528
	ds_read_b128 v[204:207], v143 offset:23552
	global_load_lds_dwordx4 v[156:157], off
	v_lshl_add_u64 v[186:187], s[16:17], 0, v[18:19]
	s_mov_b32 m0, s24
	s_nop 0
	global_load_lds_dwordx4 v[186:187], off
	s_barrier
	s_waitcnt lgkmcnt(0)
	s_setprio 1
	s_waitcnt lgkmcnt(0)
	v_mfma_f32_16x16x32_bf16 v[66:69], v[144:147], v[170:173], v[66:69]
	v_mfma_f32_16x16x32_bf16 v[62:65], v[162:165], v[170:173], v[62:65]
	v_mfma_f32_16x16x32_bf16 v[50:53], v[144:147], v[178:181], v[50:53]
	v_mfma_f32_16x16x32_bf16 v[46:49], v[162:165], v[178:181], v[46:49]
	v_mfma_f32_16x16x32_bf16 v[34:37], v[144:147], v[192:195], v[34:37]
	v_mfma_f32_16x16x32_bf16 v[30:33], v[162:165], v[192:195], v[30:33]
	v_mfma_f32_16x16x32_bf16 v[12:15], v[144:147], v[200:203], v[12:15]
	v_mfma_f32_16x16x32_bf16 v[8:11], v[162:165], v[200:203], v[8:11]
	v_mfma_f32_16x16x32_bf16 v[66:69], v[148:151], v[174:177], v[66:69]
	v_mfma_f32_16x16x32_bf16 v[62:65], v[166:169], v[174:177], v[62:65]
	v_mfma_f32_16x16x32_bf16 v[50:53], v[148:151], v[188:191], v[50:53]
	v_mfma_f32_16x16x32_bf16 v[46:49], v[166:169], v[188:191], v[46:49]
	v_mfma_f32_16x16x32_bf16 v[34:37], v[148:151], v[196:199], v[34:37]
	v_mfma_f32_16x16x32_bf16 v[30:33], v[166:169], v[196:199], v[30:33]
	v_mfma_f32_16x16x32_bf16 v[12:15], v[148:151], v[204:207], v[12:15]
	v_mfma_f32_16x16x32_bf16 v[8:11], v[166:169], v[204:207], v[8:11]
	s_setprio 0
	s_barrier
	s_add_u32 s38, s14, 0x40000
	s_addc_u32 s39, s15, 0
	s_add_i32 s37, s40, s21
	v_lshl_add_u64 v[144:145], s[38:39], 0, v[134:135]
	s_mov_b32 m0, s37
	s_nop 0
	global_load_lds_dwordx4 v[144:145], off
	v_lshl_add_u64 v[144:145], s[38:39], 0, v[18:19]
	s_add_i32 m0, s37, 0x2000
	s_nop 0
	global_load_lds_dwordx4 v[144:145], off
	s_waitcnt vmcnt(6)
	s_barrier
	s_setprio 1
	v_mfma_f32_16x16x32_bf16 v[58:61], v[208:211], v[170:173], v[58:61]
	v_mfma_f32_16x16x32_bf16 v[54:57], v[216:219], v[170:173], v[54:57]
	v_mfma_f32_16x16x32_bf16 v[42:45], v[208:211], v[178:181], v[42:45]
	v_mfma_f32_16x16x32_bf16 v[38:41], v[216:219], v[178:181], v[38:41]
	v_mfma_f32_16x16x32_bf16 v[26:29], v[208:211], v[192:195], v[26:29]
	v_mfma_f32_16x16x32_bf16 v[22:25], v[216:219], v[192:195], v[22:25]
	v_mfma_f32_16x16x32_bf16 v[4:7], v[208:211], v[200:203], v[4:7]
	v_mfma_f32_16x16x32_bf16 v[0:3], v[216:219], v[200:203], v[0:3]
	v_mfma_f32_16x16x32_bf16 v[58:61], v[212:215], v[174:177], v[58:61]
	v_mfma_f32_16x16x32_bf16 v[54:57], v[220:223], v[174:177], v[54:57]
	v_mfma_f32_16x16x32_bf16 v[42:45], v[212:215], v[188:191], v[42:45]
	v_mfma_f32_16x16x32_bf16 v[38:41], v[220:223], v[188:191], v[38:41]
	v_mfma_f32_16x16x32_bf16 v[26:29], v[212:215], v[196:199], v[26:29]
	v_mfma_f32_16x16x32_bf16 v[22:25], v[220:223], v[196:199], v[22:25]
	v_mfma_f32_16x16x32_bf16 v[4:7], v[212:215], v[204:207], v[4:7]
	v_mfma_f32_16x16x32_bf16 v[0:3], v[220:223], v[204:207], v[0:3]
	s_setprio 0
	s_add_i32 s37, 0, 0x18000
	v_add_u32_e32 v166, s37, v142
	s_barrier
	ds_read_b128 v[144:147], v166
	ds_read_b128 v[148:151], v166 offset:1024
	ds_read_b128 v[162:165], v166 offset:2048
	ds_read_b128 v[166:169], v166 offset:3072
	s_add_u32 s16, s16, 0x40000
	s_addc_u32 s17, s17, 0
	s_mov_b32 m0, s25
	v_lshl_add_u64 v[208:209], s[16:17], 0, v[134:135]
	ds_read_b128 v[170:173], v143 offset:32768
	ds_read_b128 v[174:177], v143 offset:33792
	ds_read_b128 v[178:181], v143 offset:34816
	ds_read_b128 v[188:191], v143 offset:35840
	ds_read_b128 v[192:195], v143 offset:36864
	ds_read_b128 v[196:199], v143 offset:37888
	ds_read_b128 v[200:203], v143 offset:38912
	ds_read_b128 v[204:207], v143 offset:39936
	global_load_lds_dwordx4 v[208:209], off
	v_lshl_add_u64 v[208:209], s[16:17], 0, v[18:19]
	s_mov_b32 m0, s26
	s_nop 0
	global_load_lds_dwordx4 v[208:209], off
	s_waitcnt lgkmcnt(8)
	s_barrier
; #define PG8_STAGE(bufoff, gbase, voff) do { _Pragma("unroll") for (int _i = 0; _i < 2; ++_i) \
;         __builtin_amdgcn_global_load_lds((const unsigned*)((const char*)(gbase) + (voff)[_i]), (PG8_LAS unsigned*)(lds + (bufoff) + ldsw + _i * 8192), 16, 0, 0); } while (0)
; #define PG8_LDA(dst, b, h) do { _Pragma("unroll") for (int m = 0; m < 4; ++m) _Pragma("unroll") for (int k = 0; k < 2; ++k) dst[m][k] = *(const PG8_LAS bf16x8*)(lds + PG8_SA(b, h) + aoff + m * 2048 + k * 1024); } while (0)
; #define PG8_LDB(dst, b, h) do { _Pragma("unroll") for (int n = 0; n < 2; ++n) _Pragma("unroll") for (int k = 0; k < 2; ++k) dst[n][k] = *(const PG8_LAS bf16x8*)(lds + PG8_SB(b, h) + boff + n * 2048 + k * 1024); } while (0)
; #define PG8_MMA(ai, bj, At, Bt) do { __builtin_amdgcn_s_setprio(1); _Pragma("unroll") for (int m = 0; m < 4; ++m) _Pragma("unroll") for (int n = 0; n < 2; ++n) _Pragma("unroll") for (int k = 0; k < 2; ++k) \
;         acc[ai][bj][m][n] = __builtin_amdgcn_mfma_f32_16x16x32_bf16(Bt[n][k], At[m][k], acc[ai][bj][m][n], 0, 0, 0); __builtin_amdgcn_s_setprio(0); } while (0)
; #define PG8_WAIT_V(n) asm volatile("s_waitcnt vmcnt(" #n ")" ::: "memory")
; #define PG8_WAIT_L(n) asm volatile("s_waitcnt lgkmcnt(" #n ")" ::: "memory")
; #define PG8_BAR __builtin_amdgcn_s_barrier()
; #define PG8_SCHED __builtin_amdgcn_sched_barrier(0)
; template <class Epi, class Sched>
; __device__ __forceinline__ void gemm_phase(PG8_LAS unsigned char* lds, const Gemm g, const Sched& S, const Epi& E) {
;     ...
;             PG8_BAR; PG8_WAIT_L(0); PG8_MMA(1, 0, At, B0); PG8_BAR; PG8_SCHED;
;             PG8_STAGE(PG8_SB(0, 1), b2 + hstep, voffB);
;             PG8_WAIT_V(6); PG8_BAR; PG8_MMA(1, 1, At, B1); PG8_BAR;
;             PG8_LDB(B0, 1, 0); PG8_SCHED; PG8_LDA(At, 1, 0); PG8_STAGE(PG8_SA(0, 1), a2 + hstep, voffA);
;             PG8_WAIT_L(8); PG8_BAR; PG8_WAIT_L(0); PG8_MMA(0, 0, At, B0); PG8_BAR; PG8_SCHED;
;             PG8_LDB(B1, 1, 1); PG8_STAGE(PG8_SB(1, 0), b3, voffB);
;             PG8_BAR; PG8_WAIT_L(0); PG8_MMA(0, 1, At, B1); PG8_BAR;
;             PG8_LDA(At, 1, 1); PG8_STAGE(PG8_SA(1, 0), a3, voffA);
;             PG8_BAR; PG8_WAIT_L(0); PG8_MMA(1, 0, At, B0); PG8_BAR; PG8_SCHED;
;             PG8_STAGE(PG8_SB(1, 1), b3 + hstep, voffB);
;             PG8_WAIT_V(6); PG8_BAR; PG8_MMA(1, 1, At, B1); PG8_BAR;
	s_waitcnt lgkmcnt(0)
	s_setprio 1
	s_waitcnt lgkmcnt(0)
	v_mfma_f32_16x16x32_bf16 v[130:133], v[144:147], v[170:173], v[130:133]
	v_mfma_f32_16x16x32_bf16 v[126:129], v[162:165], v[170:173], v[126:129]
	v_mfma_f32_16x16x32_bf16 v[114:117], v[144:147], v[178:181], v[114:117]
	v_mfma_f32_16x16x32_bf16 v[110:113], v[162:165], v[178:181], v[110:113]
	v_mfma_f32_16x16x32_bf16 v[98:101], v[144:147], v[192:195], v[98:101]
	v_mfma_f32_16x16x32_bf16 v[94:97], v[162:165], v[192:195], v[94:97]
	v_mfma_f32_16x16x32_bf16 v[82:85], v[144:147], v[200:203], v[82:85]
	v_mfma_f32_16x16x32_bf16 v[78:81], v[162:165], v[200:203], v[78:81]
	v_mfma_f32_16x16x32_bf16 v[130:133], v[148:151], v[174:177], v[130:133]
	v_mfma_f32_16x16x32_bf16 v[126:129], v[166:169], v[174:177], v[126:129]
	v_mfma_f32_16x16x32_bf16 v[114:117], v[148:151], v[188:191], v[114:117]
	v_mfma_f32_16x16x32_bf16 v[110:113], v[166:169], v[188:191], v[110:113]
	v_mfma_f32_16x16x32_bf16 v[98:101], v[148:151], v[196:199], v[98:101]
	v_mfma_f32_16x16x32_bf16 v[94:97], v[166:169], v[196:199], v[94:97]
	v_mfma_f32_16x16x32_bf16 v[82:85], v[148:151], v[204:207], v[82:85]
	v_mfma_f32_16x16x32_bf16 v[78:81], v[166:169], v[204:207], v[78:81]
	s_setprio 0
	s_barrier
	s_add_i32 s16, 0, 0x1c000
	s_add_i32 s17, s37, s21
	v_add_u32_e32 v220, s16, v142
	v_lshl_add_u64 v[140:141], v[140:141], 0, s[42:43]
	s_mov_b32 m0, s17
	ds_read_b128 v[208:211], v220
	ds_read_b128 v[212:215], v220 offset:1024
	ds_read_b128 v[216:219], v220 offset:2048
	ds_read_b128 v[220:223], v220 offset:3072
	global_load_lds_dwordx4 v[140:141], off
	v_lshl_add_u64 v[140:141], v[154:155], 0, s[42:43]
	s_add_i32 m0, s17, 0x2000
	s_nop 0
	global_load_lds_dwordx4 v[140:141], off
	s_barrier
	s_waitcnt lgkmcnt(0)
	s_setprio 1
	s_waitcnt lgkmcnt(0)
	v_mfma_f32_16x16x32_bf16 v[122:125], v[208:211], v[170:173], v[122:125]
	v_mfma_f32_16x16x32_bf16 v[118:121], v[216:219], v[170:173], v[118:121]
	v_mfma_f32_16x16x32_bf16 v[106:109], v[208:211], v[178:181], v[106:109]
	v_mfma_f32_16x16x32_bf16 v[102:105], v[216:219], v[178:181], v[102:105]
	v_mfma_f32_16x16x32_bf16 v[90:93], v[208:211], v[192:195], v[90:93]
	v_mfma_f32_16x16x32_bf16 v[86:89], v[216:219], v[192:195], v[86:89]
	v_mfma_f32_16x16x32_bf16 v[74:77], v[208:211], v[200:203], v[74:77]
	v_mfma_f32_16x16x32_bf16 v[70:73], v[216:219], v[200:203], v[70:73]
	v_mfma_f32_16x16x32_bf16 v[122:125], v[212:215], v[174:177], v[122:125]
	v_mfma_f32_16x16x32_bf16 v[118:121], v[220:223], v[174:177], v[118:121]
	v_mfma_f32_16x16x32_bf16 v[106:109], v[212:215], v[188:191], v[106:109]
	v_mfma_f32_16x16x32_bf16 v[102:105], v[220:223], v[188:191], v[102:105]
	v_mfma_f32_16x16x32_bf16 v[90:93], v[212:215], v[196:199], v[90:93]
	v_mfma_f32_16x16x32_bf16 v[86:89], v[220:223], v[196:199], v[86:89]
	v_mfma_f32_16x16x32_bf16 v[74:77], v[212:215], v[204:207], v[74:77]
	v_mfma_f32_16x16x32_bf16 v[70:73], v[220:223], v[204:207], v[70:73]
	s_setprio 0
	s_mov_b32 m0, s27
	v_lshl_add_u64 v[140:141], v[156:157], 0, s[42:43]
	s_barrier
	ds_read_b128 v[170:173], v143 offset:49152
	ds_read_b128 v[174:177], v143 offset:50176
	ds_read_b128 v[178:181], v143 offset:51200
	ds_read_b128 v[188:191], v143 offset:52224
	ds_read_b128 v[192:195], v143 offset:53248
	ds_read_b128 v[196:199], v143 offset:54272
	ds_read_b128 v[200:203], v143 offset:55296
	ds_read_b128 v[204:207], v143 offset:56320
	global_load_lds_dwordx4 v[140:141], off
	v_lshl_add_u64 v[140:141], v[186:187], 0, s[42:43]
	s_mov_b32 m0, s28
	s_nop 0
	global_load_lds_dwordx4 v[140:141], off
	s_barrier
	s_waitcnt lgkmcnt(0)
	s_setprio 1
	s_waitcnt lgkmcnt(0)
	v_mfma_f32_16x16x32_bf16 v[66:69], v[144:147], v[170:173], v[66:69]
	v_mfma_f32_16x16x32_bf16 v[62:65], v[162:165], v[170:173], v[62:65]
	v_mfma_f32_16x16x32_bf16 v[50:53], v[144:147], v[178:181], v[50:53]
	v_mfma_f32_16x16x32_bf16 v[46:49], v[162:165], v[178:181], v[46:49]
	v_mfma_f32_16x16x32_bf16 v[34:37], v[144:147], v[192:195], v[34:37]
	v_mfma_f32_16x16x32_bf16 v[30:33], v[162:165], v[192:195], v[30:33]
	v_mfma_f32_16x16x32_bf16 v[12:15], v[144:147], v[200:203], v[12:15]
	v_mfma_f32_16x16x32_bf16 v[8:11], v[162:165], v[200:203], v[8:11]
	v_mfma_f32_16x16x32_bf16 v[66:69], v[148:151], v[174:177], v[66:69]
	v_mfma_f32_16x16x32_bf16 v[62:65], v[166:169], v[174:177], v[62:65]
	v_mfma_f32_16x16x32_bf16 v[50:53], v[148:151], v[188:191], v[50:53]
	v_mfma_f32_16x16x32_bf16 v[46:49], v[166:169], v[188:191], v[46:49]
	v_mfma_f32_16x16x32_bf16 v[34:37], v[148:151], v[196:199], v[34:37]
	v_mfma_f32_16x16x32_bf16 v[30:33], v[166:169], v[196:199], v[30:33]
	v_mfma_f32_16x16x32_bf16 v[12:15], v[148:151], v[204:207], v[12:15]
	v_mfma_f32_16x16x32_bf16 v[8:11], v[166:169], v[204:207], v[8:11]
	s_setprio 0
	s_barrier
	s_add_u32 s14, s14, 0x40080
	s_addc_u32 s15, s15, 0
	s_add_i32 s16, s16, s21
	v_lshl_add_u64 v[140:141], s[14:15], 0, v[134:135]
	s_mov_b32 m0, s16
	s_nop 0
	global_load_lds_dwordx4 v[140:141], off
	v_lshl_add_u64 v[140:141], s[14:15], 0, v[18:19]
	s_add_i32 m0, s16, 0x2000
	s_nop 0
	global_load_lds_dwordx4 v[140:141], off
	s_waitcnt vmcnt(6)
	s_barrier
; #define PG8_BAR __builtin_amdgcn_s_barrier()
; template <class Epi, class Sched>
; __device__ __forceinline__ void gemm_phase(PG8_LAS unsigned char* lds, const Gemm g, const Sched& S, const Epi& E) {
;     ...
;         for (int t = 0; t < nt; t += 2) {
;             const bool last = (t == nt - 2);
;             const char* a1 = cA + (size_t)(t + 1) * kstep;
;             const char* a2 = last ? nA : cA + (size_t)(t + 2) * kstep; const char* b2 = last ? nB : cB + (size_t)(t + 2) * kstep;
;             const char* a3 = a2 + kstep; const char* b3 = b2 + kstep;
;             if (last && has_next) S.a_ready(nxt);
;             if constexpr (Epi::MIDK) { if (t == nt / 2) E.mid(acc, cur, wr, wc, fr, fq); }
;             PG8_LDB(B0, 0, 0); PG8_SCHED; PG8_LDA(At, 0, 0); PG8_STAGE(PG8_SA(1, 1), a1 + hstep, voffA);
;             PG8_WAIT_L(8); PG8_BAR; PG8_WAIT_L(0); PG8_MMA(0, 0, At, B0); PG8_BAR; PG8_SCHED;
;             PG8_LDB(B1, 0, 1); PG8_STAGE(PG8_SB(0, 0), b2, voffB);
;             PG8_BAR; PG8_WAIT_L(0); PG8_MMA(0, 1, At, B1); PG8_BAR;
;             PG8_LDA(At, 0, 1); PG8_STAGE(PG8_SA(0, 0), a2, voffA);
;             PG8_BAR; PG8_WAIT_L(0); PG8_MMA(1, 0, At, B0); PG8_BAR; PG8_SCHED;
;             PG8_STAGE(PG8_SB(0, 1), b2 + hstep, voffB);
;             PG8_WAIT_V(6); PG8_BAR; PG8_MMA(1, 1, At, B1); PG8_BAR;
;             PG8_LDB(B0, 1, 0); PG8_SCHED; PG8_LDA(At, 1, 0); PG8_STAGE(PG8_SA(0, 1), a2 + hstep, voffA);
;             PG8_WAIT_L(8); PG8_BAR; PG8_WAIT_L(0); PG8_MMA(0, 0, At, B0); PG8_BAR; PG8_SCHED;
;             PG8_LDB(B1, 1, 1); PG8_STAGE(PG8_SB(1, 0), b3, voffB);
;             PG8_BAR; PG8_WAIT_L(0); PG8_MMA(0, 1, At, B1); PG8_BAR;
;             PG8_LDA(At, 1, 1); PG8_STAGE(PG8_SA(1, 0), a3, voffA);
;             PG8_BAR; PG8_WAIT_L(0); PG8_MMA(1, 0, At, B0); PG8_BAR; PG8_SCHED;
;             PG8_STAGE(PG8_SB(1, 1), b3 + hstep, voffB);
;             PG8_WAIT_V(6); PG8_BAR; PG8_MMA(1, 1, At, B1); PG8_BAR;
;         }
;         if constexpr (!Epi::AFTER_DRAIN) { E(acc, cur, wr, wc, fr, fq); S.done(cur); }
;         if (!has_next) break;
;   DI void operator()(const f32x4 (&acc)[2][2][4][2], const pg8::Unit& u, int wr, int wc, int fr, int fq) const {
;     ...
;             } else {
;               f32x4 x = *reinterpret_cast<const f32x4*>(p.out + idx);
;               x = x * ALPHA + a;
;               *reinterpret_cast<f32x4*>(p.out + idx) = x;
;             }
	s_setprio 1
	v_mfma_f32_16x16x32_bf16 v[58:61], v[208:211], v[170:173], v[58:61]
	v_mfma_f32_16x16x32_bf16 v[54:57], v[216:219], v[170:173], v[54:57]
	v_mfma_f32_16x16x32_bf16 v[42:45], v[208:211], v[178:181], v[42:45]
	v_mfma_f32_16x16x32_bf16 v[38:41], v[216:219], v[178:181], v[38:41]
	v_mfma_f32_16x16x32_bf16 v[26:29], v[208:211], v[192:195], v[26:29]
	v_mfma_f32_16x16x32_bf16 v[22:25], v[216:219], v[192:195], v[22:25]
	v_mfma_f32_16x16x32_bf16 v[4:7], v[208:211], v[200:203], v[4:7]
	v_mfma_f32_16x16x32_bf16 v[0:3], v[216:219], v[200:203], v[0:3]
	v_mfma_f32_16x16x32_bf16 v[58:61], v[212:215], v[174:177], v[58:61]
	v_mfma_f32_16x16x32_bf16 v[54:57], v[220:223], v[174:177], v[54:57]
	v_mfma_f32_16x16x32_bf16 v[42:45], v[212:215], v[188:191], v[42:45]
	v_mfma_f32_16x16x32_bf16 v[38:41], v[220:223], v[188:191], v[38:41]
	v_mfma_f32_16x16x32_bf16 v[26:29], v[212:215], v[196:199], v[26:29]
	v_mfma_f32_16x16x32_bf16 v[22:25], v[220:223], v[196:199], v[22:25]
	v_mfma_f32_16x16x32_bf16 v[4:7], v[212:215], v[204:207], v[4:7]
	v_mfma_f32_16x16x32_bf16 v[0:3], v[220:223], v[204:207], v[0:3]
	s_setprio 0
	s_add_i32 s36, s36, 2
	s_add_u32 s12, s12, 0x100
	s_addc_u32 s13, s13, 0
	s_add_u32 s34, s34, 0x100
	s_addc_u32 s35, s35, 0
	s_cmp_gt_u32 s36, 13
	s_barrier
	s_cbranch_scc0 .LBB0_2754
	v_readlane_b32 s12, v251, 8
	s_cmp_eq_u32 s12, 0
	s_cbranch_scc1 .Llz_plain
	v_lshl_add_u32 v140, s10, 8, v21
	s_lshl_b32 s10, s11, 10
	v_readlane_b32 s14, v249, 4
	v_readlane_b32 s15, v249, 5
	v_readlane_b32 s13, v251, 6
	s_mov_b32 s16, 0x3fd744fd
	v_and_b32_e32 v147, 63, v153
	v_and_b32_e32 v148, 15, v153
	v_lshrrev_b32_e32 v149, 3, v147
	s_add_i32 s10, s10, s13
	s_add_i32 s12, s12, -1
	s_lshl_b32 s12, s12, 12
	v_sub_u32_e32 v140, v140, v148
	v_add_u32_e32 v140, v140, v149
	v_and_b32_e32 v146, 7, v153
	v_lshlrev_b32_e32 v141, 3, v140
	v_lshl_add_u32 v146, v146, 4, s10
	v_lshl_add_u32 v140, v140, 12, v146
	v_lshrrev_b32_e32 v144, 6, v153
	v_lshlrev_b32_e32 v144, 11, v144
	v_add_u32_e32 v144, 0x20000, v144
	v_lshl_add_u32 v145, v149, 6, v144
	v_lshl_add_u32 v144, v148, 6, v144
	v_bfe_u32 v148, v153, 4, 2
	v_lshl_add_u32 v144, v148, 4, v144
	v_bfe_u32 v148, v153, 2, 1
	v_lshl_add_u32 v145, v148, 10, v145
	v_and_b32_e32 v148, 3, v153
	v_lshl_add_u32 v145, v148, 4, v145
	v_readlane_b32 s72, v249, 38
	v_readlane_b32 s73, v249, 39
	v_readlane_b32 s74, v249, 40
	v_readlane_b32 s75, v249, 41
	v_readlane_b32 s76, v249, 0
	v_readlane_b32 s77, v249, 1
	s_add_u32 s72, s72, s12
	s_addc_u32 s73, s73, 0
	s_add_u32 s74, s74, s12
	s_addc_u32 s75, s75, 0
	s_add_u32 s76, s76, 0x2b234000
	s_addc_u32 s77, s77, 0
	s_add_u32 s56, s14, 0x0
	s_addc_u32 s57, s15, 0
	s_add_u32 s78, s14, 0x8000
	s_addc_u32 s79, s15, 0
	s_add_u32 s58, s14, 0x10000
	s_addc_u32 s59, s15, 0
	s_add_u32 s80, s14, 0x18000
	s_addc_u32 s81, s15, 0
	s_add_u32 s60, s14, 0x20000
	s_addc_u32 s61, s15, 0
	s_add_u32 s82, s14, 0x28000
	s_addc_u32 s83, s15, 0
	s_add_u32 s62, s14, 0x30000
	s_addc_u32 s63, s15, 0
	s_add_u32 s84, s14, 0x38000
	s_addc_u32 s85, s15, 0
	s_add_u32 s64, s14, 0x80000
	s_addc_u32 s65, s15, 0
	s_add_u32 s86, s14, 0x88000
	s_addc_u32 s87, s15, 0
	s_add_u32 s66, s14, 0x90000
	s_addc_u32 s67, s15, 0
	s_add_u32 s88, s14, 0x98000
	s_addc_u32 s89, s15, 0
	s_add_u32 s68, s14, 0xa0000
	s_addc_u32 s69, s15, 0
	s_add_u32 s90, s14, 0xa8000
	s_addc_u32 s91, s15, 0
	s_add_u32 s70, s14, 0xb0000
	s_addc_u32 s71, s15, 0
	s_add_u32 s92, s14, 0xb8000
	s_addc_u32 s93, s15, 0
	s_nop 1
	global_load_dwordx2 v[174:175], v141, s[76:77] offset:0
	global_load_dwordx2 v[176:177], v141, s[76:77] offset:64
	global_load_dwordx2 v[178:179], v141, s[76:77] offset:128
	global_load_dwordx2 v[180:181], v141, s[76:77] offset:192
	global_load_dwordx4 v[154:157], v146, s[72:73]
	global_load_dwordx4 v[162:165], v146, s[74:75]
	global_load_dwordx4 v[166:169], v146, s[72:73] offset:512
	global_load_dwordx4 v[170:173], v146, s[74:75] offset:512
	global_load_dwordx4 v[204:207], v140, s[56:57]
	global_load_dwordx4 v[208:211], v140, s[78:79]
	global_load_dwordx4 v[212:215], v140, s[56:57] offset:512
	global_load_dwordx4 v[216:219], v140, s[78:79] offset:512
	global_load_dwordx4 v[220:223], v140, s[58:59]
	global_load_dwordx4 v[224:227], v140, s[80:81]
	global_load_dwordx4 v[228:231], v140, s[58:59] offset:512
	global_load_dwordx4 v[232:235], v140, s[80:81] offset:512
	global_load_dwordx4 v[236:239], v140, s[60:61]
	global_load_dwordx4 v[240:243], v140, s[82:83]
	global_load_dwordx4 v[244:247], v140, s[60:61] offset:512
	ds_write_b128 v144, v[130:133]
	ds_write_b128 v144, v[126:129] offset:1024
	ds_read_b128 v[186:189], v145
	ds_read_b128 v[190:193], v145 offset:512
	ds_write_b128 v144, v[122:125]
	ds_write_b128 v144, v[118:121] offset:1024
	ds_read_b128 v[194:197], v145
	ds_read_b128 v[198:201], v145 offset:512
	s_waitcnt lgkmcnt(4)
	s_waitcnt vmcnt(10)
	v_pk_add_f32 v[204:205], v[204:205], v[174:175] op_sel_hi:[1,0] neg_lo:[0,1] neg_hi:[0,1]
	v_pk_add_f32 v[206:207], v[206:207], v[174:175] op_sel_hi:[1,0] neg_lo:[0,1] neg_hi:[0,1]
	v_pk_mul_f32 v[204:205], v[204:205], v[174:175] op_sel:[0,1] op_sel_hi:[1,1]
	v_pk_mul_f32 v[206:207], v[206:207], v[174:175] op_sel:[0,1] op_sel_hi:[1,1]
	v_pk_fma_f32 v[204:205], v[204:205], v[154:155], v[162:163]
	v_pk_fma_f32 v[206:207], v[206:207], v[156:157], v[164:165]
	v_pk_fma_f32 v[186:187], v[204:205], s[16:17], v[186:187] op_sel_hi:[1,0,1]
	v_pk_fma_f32 v[188:189], v[206:207], s[16:17], v[188:189] op_sel_hi:[1,0,1]
	global_store_dwordx4 v140, v[186:189], s[56:57]
	global_load_dwordx4 v[204:207], v140, s[82:83] offset:512
	s_waitcnt vmcnt(11)
; DI bf16x4 pack4(float a, float b, float c, float d) { u32x2v u; u.x = pk2(a, b); u.y = pk2(c, d); return __builtin_bit_cast(bf16x4, u); }
; DI void ln_rows2(const float* s0, const float* s1, const float* g, const float* b, float* d0, bf16_t* db0, float* d1, bf16_t* db1, int lane) {
;     ...
;   for (int i = 0; i < 4; ++i) {
;     const float4 gg = reinterpret_cast<const float4*>(g)[lane + 64 * i], bb = reinterpret_cast<const float4*>(b)[lane + 64 * i];
;     float4 o;
;     o.x = (v0[i].x - mu0) * r0 * gg.x + bb.x; o.y = (v0[i].y - mu0) * r0 * gg.y + bb.y; o.z = (v0[i].z - mu0) * r0 * gg.z + bb.z; o.w = (v0[i].w - mu0) * r0 * gg.w + bb.w;
;     reinterpret_cast<float4*>(d0)[lane + 64 * i] = o; st4(db0 + 4 * (lane + 64 * i), pack4(o.x, o.y, o.z, o.w));
;   DI void operator()(const f32x4 (&acc)[2][2][4][2], const pg8::Unit& u, int wr, int wc, int fr, int fq) const {
;     bf16_t* MERGED = (reinterpret_cast<bf16_t*>(p.ws + OFF_GA));
; #pragma unroll
;     for (int ai = 0; ai < 2; ++ai)
; #pragma unroll
;       for (int m = 0; m < 4; ++m) {
;         const int row = u.pm * 256 + 128 * ai + 64 * wr + 16 * m + fr;
; #pragma unroll
;         for (int bj = 0; bj < 2; ++bj)
; #pragma unroll
;           for (int n = 0; n < 2; ++n) {
;             const size_t idx = (size_t)row * 1024 + u.pn * 256 + 128 * bj + 32 * wc + 16 * n + 4 * fq;
;             const f32x4 a = acc[ai][bj][m][n];
;             if (MODE == 0) {
;               const unsigned g = *reinterpret_cast<const unsigned*>(reinterpret_cast<const unsigned char*>(p.ws + OFF_RB) + idx);
;               const float k = 1.f / 255.f;
;               st4(MERGED + idx, pack4((float)(g & 255u) * k * a[0], (float)((g >> 8) & 255u) * k * a[1], (float)((g >> 16) & 255u) * k * a[2], (float)(g >> 24) * k * a[3]));
;             } else {
;               f32x4 x = *reinterpret_cast<const f32x4*>(p.out + idx);
;               x = x * ALPHA + a;
;               *reinterpret_cast<f32x4*>(p.out + idx) = x;
;             }
;           }
;       }
;   }
	v_pk_add_f32 v[208:209], v[208:209], v[176:177] op_sel_hi:[1,0] neg_lo:[0,1] neg_hi:[0,1]
	v_pk_add_f32 v[210:211], v[210:211], v[176:177] op_sel_hi:[1,0] neg_lo:[0,1] neg_hi:[0,1]
	v_pk_mul_f32 v[208:209], v[208:209], v[176:177] op_sel:[0,1] op_sel_hi:[1,1]
	v_pk_mul_f32 v[210:211], v[210:211], v[176:177] op_sel:[0,1] op_sel_hi:[1,1]
	v_pk_fma_f32 v[208:209], v[208:209], v[154:155], v[162:163]
	v_pk_fma_f32 v[210:211], v[210:211], v[156:157], v[164:165]
	v_pk_fma_f32 v[190:191], v[208:209], s[16:17], v[190:191] op_sel_hi:[1,0,1]
	v_pk_fma_f32 v[192:193], v[210:211], s[16:17], v[192:193] op_sel_hi:[1,0,1]
	global_store_dwordx4 v140, v[190:193], s[78:79]
	global_load_dwordx4 v[208:211], v140, s[62:63]
	ds_write_b128 v144, v[114:117]
	ds_write_b128 v144, v[110:113] offset:1024
	ds_read_b128 v[186:189], v145
	ds_read_b128 v[190:193], v145 offset:512
	s_waitcnt lgkmcnt(4)
	s_waitcnt vmcnt(12)
	v_pk_add_f32 v[212:213], v[212:213], v[174:175] op_sel_hi:[1,0] neg_lo:[0,1] neg_hi:[0,1]
	v_pk_add_f32 v[214:215], v[214:215], v[174:175] op_sel_hi:[1,0] neg_lo:[0,1] neg_hi:[0,1]
	v_pk_mul_f32 v[212:213], v[212:213], v[174:175] op_sel:[0,1] op_sel_hi:[1,1]
	v_pk_mul_f32 v[214:215], v[214:215], v[174:175] op_sel:[0,1] op_sel_hi:[1,1]
	v_pk_fma_f32 v[212:213], v[212:213], v[166:167], v[170:171]
	v_pk_fma_f32 v[214:215], v[214:215], v[168:169], v[172:173]
	v_pk_fma_f32 v[194:195], v[212:213], s[16:17], v[194:195] op_sel_hi:[1,0,1]
	v_pk_fma_f32 v[196:197], v[214:215], s[16:17], v[196:197] op_sel_hi:[1,0,1]
	global_store_dwordx4 v140, v[194:197], s[56:57] offset:512
	global_load_dwordx4 v[212:215], v140, s[84:85]
	s_waitcnt vmcnt(13)
	v_pk_add_f32 v[216:217], v[216:217], v[176:177] op_sel_hi:[1,0] neg_lo:[0,1] neg_hi:[0,1]
	v_pk_add_f32 v[218:219], v[218:219], v[176:177] op_sel_hi:[1,0] neg_lo:[0,1] neg_hi:[0,1]
	v_pk_mul_f32 v[216:217], v[216:217], v[176:177] op_sel:[0,1] op_sel_hi:[1,1]
	v_pk_mul_f32 v[218:219], v[218:219], v[176:177] op_sel:[0,1] op_sel_hi:[1,1]
	v_pk_fma_f32 v[216:217], v[216:217], v[166:167], v[170:171]
	v_pk_fma_f32 v[218:219], v[218:219], v[168:169], v[172:173]
	v_pk_fma_f32 v[198:199], v[216:217], s[16:17], v[198:199] op_sel_hi:[1,0,1]
	v_pk_fma_f32 v[200:201], v[218:219], s[16:17], v[200:201] op_sel_hi:[1,0,1]
	global_store_dwordx4 v140, v[198:201], s[78:79] offset:512
	global_load_dwordx4 v[216:219], v140, s[62:63] offset:512
	global_load_dwordx2 v[174:175], v141, s[76:77] offset:256
	global_load_dwordx2 v[176:177], v141, s[76:77] offset:320
	ds_write_b128 v144, v[106:109]
	ds_write_b128 v144, v[102:105] offset:1024
	ds_read_b128 v[194:197], v145
	ds_read_b128 v[198:201], v145 offset:512
	s_waitcnt lgkmcnt(4)
	s_waitcnt vmcnt(16)
	v_pk_add_f32 v[220:221], v[220:221], v[178:179] op_sel_hi:[1,0] neg_lo:[0,1] neg_hi:[0,1]
	v_pk_add_f32 v[222:223], v[222:223], v[178:179] op_sel_hi:[1,0] neg_lo:[0,1] neg_hi:[0,1]
	v_pk_mul_f32 v[220:221], v[220:221], v[178:179] op_sel:[0,1] op_sel_hi:[1,1]
	v_pk_mul_f32 v[222:223], v[222:223], v[178:179] op_sel:[0,1] op_sel_hi:[1,1]
	v_pk_fma_f32 v[220:221], v[220:221], v[154:155], v[162:163]
	v_pk_fma_f32 v[222:223], v[222:223], v[156:157], v[164:165]
	v_pk_fma_f32 v[186:187], v[220:221], s[16:17], v[186:187] op_sel_hi:[1,0,1]
	v_pk_fma_f32 v[188:189], v[222:223], s[16:17], v[188:189] op_sel_hi:[1,0,1]
	global_store_dwordx4 v140, v[186:189], s[58:59]
	global_load_dwordx4 v[220:223], v140, s[84:85] offset:512
	s_waitcnt vmcnt(17)
	v_pk_add_f32 v[224:225], v[224:225], v[180:181] op_sel_hi:[1,0] neg_lo:[0,1] neg_hi:[0,1]
	v_pk_add_f32 v[226:227], v[226:227], v[180:181] op_sel_hi:[1,0] neg_lo:[0,1] neg_hi:[0,1]
	v_pk_mul_f32 v[224:225], v[224:225], v[180:181] op_sel:[0,1] op_sel_hi:[1,1]
	v_pk_mul_f32 v[226:227], v[226:227], v[180:181] op_sel:[0,1] op_sel_hi:[1,1]
	v_pk_fma_f32 v[224:225], v[224:225], v[154:155], v[162:163]
	v_pk_fma_f32 v[226:227], v[226:227], v[156:157], v[164:165]
	v_pk_fma_f32 v[190:191], v[224:225], s[16:17], v[190:191] op_sel_hi:[1,0,1]
	v_pk_fma_f32 v[192:193], v[226:227], s[16:17], v[192:193] op_sel_hi:[1,0,1]
	global_store_dwordx4 v140, v[190:193], s[80:81]
	global_load_dwordx4 v[224:227], v140, s[64:65]
	ds_write_b128 v144, v[98:101]
	ds_write_b128 v144, v[94:97] offset:1024
	ds_read_b128 v[186:189], v145
	ds_read_b128 v[190:193], v145 offset:512
	s_waitcnt lgkmcnt(4)
	s_waitcnt vmcnt(18)
	v_pk_add_f32 v[228:229], v[228:229], v[178:179] op_sel_hi:[1,0] neg_lo:[0,1] neg_hi:[0,1]
	v_pk_add_f32 v[230:231], v[230:231], v[178:179] op_sel_hi:[1,0] neg_lo:[0,1] neg_hi:[0,1]
	v_pk_mul_f32 v[228:229], v[228:229], v[178:179] op_sel:[0,1] op_sel_hi:[1,1]
	v_pk_mul_f32 v[230:231], v[230:231], v[178:179] op_sel:[0,1] op_sel_hi:[1,1]
	v_pk_fma_f32 v[228:229], v[228:229], v[166:167], v[170:171]
	v_pk_fma_f32 v[230:231], v[230:231], v[168:169], v[172:173]
	v_pk_fma_f32 v[194:195], v[228:229], s[16:17], v[194:195] op_sel_hi:[1,0,1]
	v_pk_fma_f32 v[196:197], v[230:231], s[16:17], v[196:197] op_sel_hi:[1,0,1]
	global_store_dwordx4 v140, v[194:197], s[58:59] offset:512
	global_load_dwordx4 v[228:231], v140, s[86:87]
	s_waitcnt vmcnt(19)
	v_pk_add_f32 v[232:233], v[232:233], v[180:181] op_sel_hi:[1,0] neg_lo:[0,1] neg_hi:[0,1]
	v_pk_add_f32 v[234:235], v[234:235], v[180:181] op_sel_hi:[1,0] neg_lo:[0,1] neg_hi:[0,1]
	v_pk_mul_f32 v[232:233], v[232:233], v[180:181] op_sel:[0,1] op_sel_hi:[1,1]
	v_pk_mul_f32 v[234:235], v[234:235], v[180:181] op_sel:[0,1] op_sel_hi:[1,1]
	v_pk_fma_f32 v[232:233], v[232:233], v[166:167], v[170:171]
	v_pk_fma_f32 v[234:235], v[234:235], v[168:169], v[172:173]
	v_pk_fma_f32 v[198:199], v[232:233], s[16:17], v[198:199] op_sel_hi:[1,0,1]
	v_pk_fma_f32 v[200:201], v[234:235], s[16:17], v[200:201] op_sel_hi:[1,0,1]
	global_store_dwordx4 v140, v[198:201], s[80:81] offset:512
	global_load_dwordx4 v[232:235], v140, s[64:65] offset:512
	global_load_dwordx2 v[178:179], v141, s[76:77] offset:384
	global_load_dwordx2 v[180:181], v141, s[76:77] offset:448
	ds_write_b128 v144, v[90:93]
	ds_write_b128 v144, v[86:89] offset:1024
	ds_read_b128 v[194:197], v145
	ds_read_b128 v[198:201], v145 offset:512
	s_waitcnt lgkmcnt(4)
; DI bf16x4 pack4(float a, float b, float c, float d) { u32x2v u; u.x = pk2(a, b); u.y = pk2(c, d); return __builtin_bit_cast(bf16x4, u); }
; DI void ln_rows2(const float* s0, const float* s1, const float* g, const float* b, float* d0, bf16_t* db0, float* d1, bf16_t* db1, int lane) {
;     ...
;   for (int i = 0; i < 4; ++i) {
;     const float4 gg = reinterpret_cast<const float4*>(g)[lane + 64 * i], bb = reinterpret_cast<const float4*>(b)[lane + 64 * i];
;     float4 o;
;     o.x = (v0[i].x - mu0) * r0 * gg.x + bb.x; o.y = (v0[i].y - mu0) * r0 * gg.y + bb.y; o.z = (v0[i].z - mu0) * r0 * gg.z + bb.z; o.w = (v0[i].w - mu0) * r0 * gg.w + bb.w;
;     reinterpret_cast<float4*>(d0)[lane + 64 * i] = o; st4(db0 + 4 * (lane + 64 * i), pack4(o.x, o.y, o.z, o.w));
;   DI void operator()(const f32x4 (&acc)[2][2][4][2], const pg8::Unit& u, int wr, int wc, int fr, int fq) const {
;     bf16_t* MERGED = (reinterpret_cast<bf16_t*>(p.ws + OFF_GA));
; #pragma unroll
;     for (int ai = 0; ai < 2; ++ai)
; #pragma unroll
;       for (int m = 0; m < 4; ++m) {
;         const int row = u.pm * 256 + 128 * ai + 64 * wr + 16 * m + fr;
; #pragma unroll
;         for (int bj = 0; bj < 2; ++bj)
; #pragma unroll
;           for (int n = 0; n < 2; ++n) {
;             const size_t idx = (size_t)row * 1024 + u.pn * 256 + 128 * bj + 32 * wc + 16 * n + 4 * fq;
;             const f32x4 a = acc[ai][bj][m][n];
;             if (MODE == 0) {
;               const unsigned g = *reinterpret_cast<const unsigned*>(reinterpret_cast<const unsigned char*>(p.ws + OFF_RB) + idx);
;               const float k = 1.f / 255.f;
;               st4(MERGED + idx, pack4((float)(g & 255u) * k * a[0], (float)((g >> 8) & 255u) * k * a[1], (float)((g >> 16) & 255u) * k * a[2], (float)(g >> 24) * k * a[3]));
;             } else {
;               f32x4 x = *reinterpret_cast<const f32x4*>(p.out + idx);
;               x = x * ALPHA + a;
;               *reinterpret_cast<f32x4*>(p.out + idx) = x;
;             }
;           }
;       }
;   }
	s_waitcnt vmcnt(11)
	v_pk_add_f32 v[236:237], v[236:237], v[174:175] op_sel_hi:[1,0] neg_lo:[0,1] neg_hi:[0,1]
	v_pk_add_f32 v[238:239], v[238:239], v[174:175] op_sel_hi:[1,0] neg_lo:[0,1] neg_hi:[0,1]
	v_pk_mul_f32 v[236:237], v[236:237], v[174:175] op_sel:[0,1] op_sel_hi:[1,1]
	v_pk_mul_f32 v[238:239], v[238:239], v[174:175] op_sel:[0,1] op_sel_hi:[1,1]
	v_pk_fma_f32 v[236:237], v[236:237], v[154:155], v[162:163]
	v_pk_fma_f32 v[238:239], v[238:239], v[156:157], v[164:165]
	v_pk_fma_f32 v[186:187], v[236:237], s[16:17], v[186:187] op_sel_hi:[1,0,1]
	v_pk_fma_f32 v[188:189], v[238:239], s[16:17], v[188:189] op_sel_hi:[1,0,1]
	global_store_dwordx4 v140, v[186:189], s[60:61]
	global_load_dwordx4 v[236:239], v140, s[86:87] offset:512
	s_waitcnt vmcnt(12)
	v_pk_add_f32 v[240:241], v[240:241], v[176:177] op_sel_hi:[1,0] neg_lo:[0,1] neg_hi:[0,1]
	v_pk_add_f32 v[242:243], v[242:243], v[176:177] op_sel_hi:[1,0] neg_lo:[0,1] neg_hi:[0,1]
	v_pk_mul_f32 v[240:241], v[240:241], v[176:177] op_sel:[0,1] op_sel_hi:[1,1]
	v_pk_mul_f32 v[242:243], v[242:243], v[176:177] op_sel:[0,1] op_sel_hi:[1,1]
	v_pk_fma_f32 v[240:241], v[240:241], v[154:155], v[162:163]
	v_pk_fma_f32 v[242:243], v[242:243], v[156:157], v[164:165]
	v_pk_fma_f32 v[190:191], v[240:241], s[16:17], v[190:191] op_sel_hi:[1,0,1]
	v_pk_fma_f32 v[192:193], v[242:243], s[16:17], v[192:193] op_sel_hi:[1,0,1]
	global_store_dwordx4 v140, v[190:193], s[82:83]
	global_load_dwordx4 v[240:243], v140, s[66:67]
	ds_write_b128 v144, v[82:85]
	ds_write_b128 v144, v[78:81] offset:1024
	ds_read_b128 v[186:189], v145
	ds_read_b128 v[190:193], v145 offset:512
	s_waitcnt lgkmcnt(4)
	s_waitcnt vmcnt(15)
	v_pk_add_f32 v[244:245], v[244:245], v[174:175] op_sel_hi:[1,0] neg_lo:[0,1] neg_hi:[0,1]
	v_pk_add_f32 v[246:247], v[246:247], v[174:175] op_sel_hi:[1,0] neg_lo:[0,1] neg_hi:[0,1]
	v_pk_mul_f32 v[244:245], v[244:245], v[174:175] op_sel:[0,1] op_sel_hi:[1,1]
	v_pk_mul_f32 v[246:247], v[246:247], v[174:175] op_sel:[0,1] op_sel_hi:[1,1]
	v_pk_fma_f32 v[244:245], v[244:245], v[166:167], v[170:171]
	v_pk_fma_f32 v[246:247], v[246:247], v[168:169], v[172:173]
	v_pk_fma_f32 v[194:195], v[244:245], s[16:17], v[194:195] op_sel_hi:[1,0,1]
	v_pk_fma_f32 v[196:197], v[246:247], s[16:17], v[196:197] op_sel_hi:[1,0,1]
	global_store_dwordx4 v140, v[194:197], s[60:61] offset:512
	global_load_dwordx4 v[244:247], v140, s[88:89]
	s_waitcnt vmcnt(16)
	v_pk_add_f32 v[204:205], v[204:205], v[176:177] op_sel_hi:[1,0] neg_lo:[0,1] neg_hi:[0,1]
	v_pk_add_f32 v[206:207], v[206:207], v[176:177] op_sel_hi:[1,0] neg_lo:[0,1] neg_hi:[0,1]
	v_pk_mul_f32 v[204:205], v[204:205], v[176:177] op_sel:[0,1] op_sel_hi:[1,1]
	v_pk_mul_f32 v[206:207], v[206:207], v[176:177] op_sel:[0,1] op_sel_hi:[1,1]
	v_pk_fma_f32 v[204:205], v[204:205], v[166:167], v[170:171]
	v_pk_fma_f32 v[206:207], v[206:207], v[168:169], v[172:173]
	v_pk_fma_f32 v[198:199], v[204:205], s[16:17], v[198:199] op_sel_hi:[1,0,1]
	v_pk_fma_f32 v[200:201], v[206:207], s[16:17], v[200:201] op_sel_hi:[1,0,1]
	global_store_dwordx4 v140, v[198:201], s[82:83] offset:512
	global_load_dwordx4 v[204:207], v140, s[66:67] offset:512
	global_load_dwordx2 v[174:175], v141, s[76:77] offset:1024
	global_load_dwordx2 v[176:177], v141, s[76:77] offset:1088
	ds_write_b128 v144, v[74:77]
	ds_write_b128 v144, v[70:73] offset:1024
	ds_read_b128 v[194:197], v145
	ds_read_b128 v[198:201], v145 offset:512
	s_waitcnt lgkmcnt(4)
	s_waitcnt vmcnt(11)
	v_pk_add_f32 v[208:209], v[208:209], v[178:179] op_sel_hi:[1,0] neg_lo:[0,1] neg_hi:[0,1]
	v_pk_add_f32 v[210:211], v[210:211], v[178:179] op_sel_hi:[1,0] neg_lo:[0,1] neg_hi:[0,1]
	v_pk_mul_f32 v[208:209], v[208:209], v[178:179] op_sel:[0,1] op_sel_hi:[1,1]
	v_pk_mul_f32 v[210:211], v[210:211], v[178:179] op_sel:[0,1] op_sel_hi:[1,1]
	v_pk_fma_f32 v[208:209], v[208:209], v[154:155], v[162:163]
	v_pk_fma_f32 v[210:211], v[210:211], v[156:157], v[164:165]
	v_pk_fma_f32 v[186:187], v[208:209], s[16:17], v[186:187] op_sel_hi:[1,0,1]
	v_pk_fma_f32 v[188:189], v[210:211], s[16:17], v[188:189] op_sel_hi:[1,0,1]
	global_store_dwordx4 v140, v[186:189], s[62:63]
	global_load_dwordx4 v[208:211], v140, s[88:89] offset:512
	s_waitcnt vmcnt(12)
	v_pk_add_f32 v[212:213], v[212:213], v[180:181] op_sel_hi:[1,0] neg_lo:[0,1] neg_hi:[0,1]
	v_pk_add_f32 v[214:215], v[214:215], v[180:181] op_sel_hi:[1,0] neg_lo:[0,1] neg_hi:[0,1]
	v_pk_mul_f32 v[212:213], v[212:213], v[180:181] op_sel:[0,1] op_sel_hi:[1,1]
	v_pk_mul_f32 v[214:215], v[214:215], v[180:181] op_sel:[0,1] op_sel_hi:[1,1]
	v_pk_fma_f32 v[212:213], v[212:213], v[154:155], v[162:163]
	v_pk_fma_f32 v[214:215], v[214:215], v[156:157], v[164:165]
	v_pk_fma_f32 v[190:191], v[212:213], s[16:17], v[190:191] op_sel_hi:[1,0,1]
	v_pk_fma_f32 v[192:193], v[214:215], s[16:17], v[192:193] op_sel_hi:[1,0,1]
	global_store_dwordx4 v140, v[190:193], s[84:85]
	global_load_dwordx4 v[212:215], v140, s[68:69]
	ds_write_b128 v144, v[66:69]
	ds_write_b128 v144, v[62:65] offset:1024
	ds_read_b128 v[186:189], v145
	ds_read_b128 v[190:193], v145 offset:512
	s_waitcnt lgkmcnt(4)
	s_waitcnt vmcnt(15)
	v_pk_add_f32 v[216:217], v[216:217], v[178:179] op_sel_hi:[1,0] neg_lo:[0,1] neg_hi:[0,1]
	v_pk_add_f32 v[218:219], v[218:219], v[178:179] op_sel_hi:[1,0] neg_lo:[0,1] neg_hi:[0,1]
	v_pk_mul_f32 v[216:217], v[216:217], v[178:179] op_sel:[0,1] op_sel_hi:[1,1]
	v_pk_mul_f32 v[218:219], v[218:219], v[178:179] op_sel:[0,1] op_sel_hi:[1,1]
	v_pk_fma_f32 v[216:217], v[216:217], v[166:167], v[170:171]
	v_pk_fma_f32 v[218:219], v[218:219], v[168:169], v[172:173]
	v_pk_fma_f32 v[194:195], v[216:217], s[16:17], v[194:195] op_sel_hi:[1,0,1]
	v_pk_fma_f32 v[196:197], v[218:219], s[16:17], v[196:197] op_sel_hi:[1,0,1]
	global_store_dwordx4 v140, v[194:197], s[62:63] offset:512
	global_load_dwordx4 v[216:219], v140, s[90:91]
	s_waitcnt vmcnt(16)
; DI bf16x4 pack4(float a, float b, float c, float d) { u32x2v u; u.x = pk2(a, b); u.y = pk2(c, d); return __builtin_bit_cast(bf16x4, u); }
; DI void ln_rows2(const float* s0, const float* s1, const float* g, const float* b, float* d0, bf16_t* db0, float* d1, bf16_t* db1, int lane) {
;     ...
;   for (int i = 0; i < 4; ++i) {
;     const float4 gg = reinterpret_cast<const float4*>(g)[lane + 64 * i], bb = reinterpret_cast<const float4*>(b)[lane + 64 * i];
;     float4 o;
;     o.x = (v0[i].x - mu0) * r0 * gg.x + bb.x; o.y = (v0[i].y - mu0) * r0 * gg.y + bb.y; o.z = (v0[i].z - mu0) * r0 * gg.z + bb.z; o.w = (v0[i].w - mu0) * r0 * gg.w + bb.w;
;     reinterpret_cast<float4*>(d0)[lane + 64 * i] = o; st4(db0 + 4 * (lane + 64 * i), pack4(o.x, o.y, o.z, o.w));
;   DI void operator()(const f32x4 (&acc)[2][2][4][2], const pg8::Unit& u, int wr, int wc, int fr, int fq) const {
;     bf16_t* MERGED = (reinterpret_cast<bf16_t*>(p.ws + OFF_GA));
; #pragma unroll
;     for (int ai = 0; ai < 2; ++ai)
; #pragma unroll
;       for (int m = 0; m < 4; ++m) {
;         const int row = u.pm * 256 + 128 * ai + 64 * wr + 16 * m + fr;
; #pragma unroll
;         for (int bj = 0; bj < 2; ++bj)
; #pragma unroll
;           for (int n = 0; n < 2; ++n) {
;             const size_t idx = (size_t)row * 1024 + u.pn * 256 + 128 * bj + 32 * wc + 16 * n + 4 * fq;
;             const f32x4 a = acc[ai][bj][m][n];
;             if (MODE == 0) {
;               const unsigned g = *reinterpret_cast<const unsigned*>(reinterpret_cast<const unsigned char*>(p.ws + OFF_RB) + idx);
;               const float k = 1.f / 255.f;
;               st4(MERGED + idx, pack4((float)(g & 255u) * k * a[0], (float)((g >> 8) & 255u) * k * a[1], (float)((g >> 16) & 255u) * k * a[2], (float)(g >> 24) * k * a[3]));
;             } else {
;               f32x4 x = *reinterpret_cast<const f32x4*>(p.out + idx);
;               x = x * ALPHA + a;
;               *reinterpret_cast<f32x4*>(p.out + idx) = x;
;             }
;           }
;       }
;   }
	v_pk_add_f32 v[220:221], v[220:221], v[180:181] op_sel_hi:[1,0] neg_lo:[0,1] neg_hi:[0,1]
	v_pk_add_f32 v[222:223], v[222:223], v[180:181] op_sel_hi:[1,0] neg_lo:[0,1] neg_hi:[0,1]
	v_pk_mul_f32 v[220:221], v[220:221], v[180:181] op_sel:[0,1] op_sel_hi:[1,1]
	v_pk_mul_f32 v[222:223], v[222:223], v[180:181] op_sel:[0,1] op_sel_hi:[1,1]
	v_pk_fma_f32 v[220:221], v[220:221], v[166:167], v[170:171]
	v_pk_fma_f32 v[222:223], v[222:223], v[168:169], v[172:173]
	v_pk_fma_f32 v[198:199], v[220:221], s[16:17], v[198:199] op_sel_hi:[1,0,1]
	v_pk_fma_f32 v[200:201], v[222:223], s[16:17], v[200:201] op_sel_hi:[1,0,1]
	global_store_dwordx4 v140, v[198:201], s[84:85] offset:512
	global_load_dwordx4 v[220:223], v140, s[68:69] offset:512
	global_load_dwordx2 v[178:179], v141, s[76:77] offset:1152
	global_load_dwordx2 v[180:181], v141, s[76:77] offset:1216
	ds_write_b128 v144, v[58:61]
	ds_write_b128 v144, v[54:57] offset:1024
	ds_read_b128 v[194:197], v145
	ds_read_b128 v[198:201], v145 offset:512
	s_waitcnt lgkmcnt(4)
	s_waitcnt vmcnt(11)
	v_pk_add_f32 v[224:225], v[224:225], v[174:175] op_sel_hi:[1,0] neg_lo:[0,1] neg_hi:[0,1]
	v_pk_add_f32 v[226:227], v[226:227], v[174:175] op_sel_hi:[1,0] neg_lo:[0,1] neg_hi:[0,1]
	v_pk_mul_f32 v[224:225], v[224:225], v[174:175] op_sel:[0,1] op_sel_hi:[1,1]
	v_pk_mul_f32 v[226:227], v[226:227], v[174:175] op_sel:[0,1] op_sel_hi:[1,1]
	v_pk_fma_f32 v[224:225], v[224:225], v[154:155], v[162:163]
	v_pk_fma_f32 v[226:227], v[226:227], v[156:157], v[164:165]
	v_pk_fma_f32 v[186:187], v[224:225], s[16:17], v[186:187] op_sel_hi:[1,0,1]
	v_pk_fma_f32 v[188:189], v[226:227], s[16:17], v[188:189] op_sel_hi:[1,0,1]
	global_store_dwordx4 v140, v[186:189], s[64:65]
	global_load_dwordx4 v[224:227], v140, s[90:91] offset:512
	s_waitcnt vmcnt(12)
	v_pk_add_f32 v[228:229], v[228:229], v[176:177] op_sel_hi:[1,0] neg_lo:[0,1] neg_hi:[0,1]
	v_pk_add_f32 v[230:231], v[230:231], v[176:177] op_sel_hi:[1,0] neg_lo:[0,1] neg_hi:[0,1]
	v_pk_mul_f32 v[228:229], v[228:229], v[176:177] op_sel:[0,1] op_sel_hi:[1,1]
	v_pk_mul_f32 v[230:231], v[230:231], v[176:177] op_sel:[0,1] op_sel_hi:[1,1]
	v_pk_fma_f32 v[228:229], v[228:229], v[154:155], v[162:163]
	v_pk_fma_f32 v[230:231], v[230:231], v[156:157], v[164:165]
	v_pk_fma_f32 v[190:191], v[228:229], s[16:17], v[190:191] op_sel_hi:[1,0,1]
	v_pk_fma_f32 v[192:193], v[230:231], s[16:17], v[192:193] op_sel_hi:[1,0,1]
	global_store_dwordx4 v140, v[190:193], s[86:87]
	global_load_dwordx4 v[228:231], v140, s[70:71]
	ds_write_b128 v144, v[50:53]
	ds_write_b128 v144, v[46:49] offset:1024
	ds_read_b128 v[186:189], v145
	ds_read_b128 v[190:193], v145 offset:512
	s_waitcnt lgkmcnt(4)
	s_waitcnt vmcnt(15)
	v_pk_add_f32 v[232:233], v[232:233], v[174:175] op_sel_hi:[1,0] neg_lo:[0,1] neg_hi:[0,1]
	v_pk_add_f32 v[234:235], v[234:235], v[174:175] op_sel_hi:[1,0] neg_lo:[0,1] neg_hi:[0,1]
	v_pk_mul_f32 v[232:233], v[232:233], v[174:175] op_sel:[0,1] op_sel_hi:[1,1]
	v_pk_mul_f32 v[234:235], v[234:235], v[174:175] op_sel:[0,1] op_sel_hi:[1,1]
	v_pk_fma_f32 v[232:233], v[232:233], v[166:167], v[170:171]
	v_pk_fma_f32 v[234:235], v[234:235], v[168:169], v[172:173]
	v_pk_fma_f32 v[194:195], v[232:233], s[16:17], v[194:195] op_sel_hi:[1,0,1]
	v_pk_fma_f32 v[196:197], v[234:235], s[16:17], v[196:197] op_sel_hi:[1,0,1]
	global_store_dwordx4 v140, v[194:197], s[64:65] offset:512
	global_load_dwordx4 v[232:235], v140, s[92:93]
	s_waitcnt vmcnt(16)
	v_pk_add_f32 v[236:237], v[236:237], v[176:177] op_sel_hi:[1,0] neg_lo:[0,1] neg_hi:[0,1]
	v_pk_add_f32 v[238:239], v[238:239], v[176:177] op_sel_hi:[1,0] neg_lo:[0,1] neg_hi:[0,1]
	v_pk_mul_f32 v[236:237], v[236:237], v[176:177] op_sel:[0,1] op_sel_hi:[1,1]
	v_pk_mul_f32 v[238:239], v[238:239], v[176:177] op_sel:[0,1] op_sel_hi:[1,1]
	v_pk_fma_f32 v[236:237], v[236:237], v[166:167], v[170:171]
	v_pk_fma_f32 v[238:239], v[238:239], v[168:169], v[172:173]
	v_pk_fma_f32 v[198:199], v[236:237], s[16:17], v[198:199] op_sel_hi:[1,0,1]
	v_pk_fma_f32 v[200:201], v[238:239], s[16:17], v[200:201] op_sel_hi:[1,0,1]
	global_store_dwordx4 v140, v[198:201], s[86:87] offset:512
	global_load_dwordx4 v[236:239], v140, s[70:71] offset:512
	global_load_dwordx2 v[174:175], v141, s[76:77] offset:1280
	global_load_dwordx2 v[176:177], v141, s[76:77] offset:1344
	ds_write_b128 v144, v[42:45]
	ds_write_b128 v144, v[38:41] offset:1024
	ds_read_b128 v[194:197], v145
	ds_read_b128 v[198:201], v145 offset:512
	s_waitcnt lgkmcnt(4)
	s_waitcnt vmcnt(11)
	v_pk_add_f32 v[240:241], v[240:241], v[178:179] op_sel_hi:[1,0] neg_lo:[0,1] neg_hi:[0,1]
	v_pk_add_f32 v[242:243], v[242:243], v[178:179] op_sel_hi:[1,0] neg_lo:[0,1] neg_hi:[0,1]
	v_pk_mul_f32 v[240:241], v[240:241], v[178:179] op_sel:[0,1] op_sel_hi:[1,1]
	v_pk_mul_f32 v[242:243], v[242:243], v[178:179] op_sel:[0,1] op_sel_hi:[1,1]
	v_pk_fma_f32 v[240:241], v[240:241], v[154:155], v[162:163]
	v_pk_fma_f32 v[242:243], v[242:243], v[156:157], v[164:165]
	v_pk_fma_f32 v[186:187], v[240:241], s[16:17], v[186:187] op_sel_hi:[1,0,1]
	v_pk_fma_f32 v[188:189], v[242:243], s[16:17], v[188:189] op_sel_hi:[1,0,1]
	global_store_dwordx4 v140, v[186:189], s[66:67]
	global_load_dwordx4 v[240:243], v140, s[92:93] offset:512
	s_waitcnt vmcnt(12)
	v_pk_add_f32 v[244:245], v[244:245], v[180:181] op_sel_hi:[1,0] neg_lo:[0,1] neg_hi:[0,1]
	v_pk_add_f32 v[246:247], v[246:247], v[180:181] op_sel_hi:[1,0] neg_lo:[0,1] neg_hi:[0,1]
	v_pk_mul_f32 v[244:245], v[244:245], v[180:181] op_sel:[0,1] op_sel_hi:[1,1]
	v_pk_mul_f32 v[246:247], v[246:247], v[180:181] op_sel:[0,1] op_sel_hi:[1,1]
	v_pk_fma_f32 v[244:245], v[244:245], v[154:155], v[162:163]
	v_pk_fma_f32 v[246:247], v[246:247], v[156:157], v[164:165]
	v_pk_fma_f32 v[190:191], v[244:245], s[16:17], v[190:191] op_sel_hi:[1,0,1]
	v_pk_fma_f32 v[192:193], v[246:247], s[16:17], v[192:193] op_sel_hi:[1,0,1]
	global_store_dwordx4 v140, v[190:193], s[88:89]
	ds_write_b128 v144, v[34:37]
	ds_write_b128 v144, v[30:33] offset:1024
	ds_read_b128 v[186:189], v145
	ds_read_b128 v[190:193], v145 offset:512
	s_waitcnt lgkmcnt(4)
; DI bf16x4 pack4(float a, float b, float c, float d) { u32x2v u; u.x = pk2(a, b); u.y = pk2(c, d); return __builtin_bit_cast(bf16x4, u); }
; DI void ln_rows2(const float* s0, const float* s1, const float* g, const float* b, float* d0, bf16_t* db0, float* d1, bf16_t* db1, int lane) {
;     ...
;   for (int i = 0; i < 4; ++i) {
;     const float4 gg = reinterpret_cast<const float4*>(g)[lane + 64 * i], bb = reinterpret_cast<const float4*>(b)[lane + 64 * i];
;     float4 o;
;     o.x = (v0[i].x - mu0) * r0 * gg.x + bb.x; o.y = (v0[i].y - mu0) * r0 * gg.y + bb.y; o.z = (v0[i].z - mu0) * r0 * gg.z + bb.z; o.w = (v0[i].w - mu0) * r0 * gg.w + bb.w;
;     reinterpret_cast<float4*>(d0)[lane + 64 * i] = o; st4(db0 + 4 * (lane + 64 * i), pack4(o.x, o.y, o.z, o.w));
;   DI void operator()(const f32x4 (&acc)[2][2][4][2], const pg8::Unit& u, int wr, int wc, int fr, int fq) const {
;     bf16_t* MERGED = (reinterpret_cast<bf16_t*>(p.ws + OFF_GA));
; #pragma unroll
;     for (int ai = 0; ai < 2; ++ai)
; #pragma unroll
;       for (int m = 0; m < 4; ++m) {
;         const int row = u.pm * 256 + 128 * ai + 64 * wr + 16 * m + fr;
; #pragma unroll
;         for (int bj = 0; bj < 2; ++bj)
; #pragma unroll
;           for (int n = 0; n < 2; ++n) {
;             const size_t idx = (size_t)row * 1024 + u.pn * 256 + 128 * bj + 32 * wc + 16 * n + 4 * fq;
;             const f32x4 a = acc[ai][bj][m][n];
;             if (MODE == 0) {
;               const unsigned g = *reinterpret_cast<const unsigned*>(reinterpret_cast<const unsigned char*>(p.ws + OFF_RB) + idx);
;               const float k = 1.f / 255.f;
;               st4(MERGED + idx, pack4((float)(g & 255u) * k * a[0], (float)((g >> 8) & 255u) * k * a[1], (float)((g >> 16) & 255u) * k * a[2], (float)(g >> 24) * k * a[3]));
;             } else {
;               f32x4 x = *reinterpret_cast<const f32x4*>(p.out + idx);
;               x = x * ALPHA + a;
;               *reinterpret_cast<f32x4*>(p.out + idx) = x;
;             }
;           }
;       }
;   }
	s_waitcnt vmcnt(14)
	v_pk_add_f32 v[204:205], v[204:205], v[178:179] op_sel_hi:[1,0] neg_lo:[0,1] neg_hi:[0,1]
	v_pk_add_f32 v[206:207], v[206:207], v[178:179] op_sel_hi:[1,0] neg_lo:[0,1] neg_hi:[0,1]
	v_pk_mul_f32 v[204:205], v[204:205], v[178:179] op_sel:[0,1] op_sel_hi:[1,1]
	v_pk_mul_f32 v[206:207], v[206:207], v[178:179] op_sel:[0,1] op_sel_hi:[1,1]
	v_pk_fma_f32 v[204:205], v[204:205], v[166:167], v[170:171]
	v_pk_fma_f32 v[206:207], v[206:207], v[168:169], v[172:173]
	v_pk_fma_f32 v[194:195], v[204:205], s[16:17], v[194:195] op_sel_hi:[1,0,1]
	v_pk_fma_f32 v[196:197], v[206:207], s[16:17], v[196:197] op_sel_hi:[1,0,1]
	global_store_dwordx4 v140, v[194:197], s[66:67] offset:512
	s_waitcnt vmcnt(14)
	v_pk_add_f32 v[208:209], v[208:209], v[180:181] op_sel_hi:[1,0] neg_lo:[0,1] neg_hi:[0,1]
	v_pk_add_f32 v[210:211], v[210:211], v[180:181] op_sel_hi:[1,0] neg_lo:[0,1] neg_hi:[0,1]
	v_pk_mul_f32 v[208:209], v[208:209], v[180:181] op_sel:[0,1] op_sel_hi:[1,1]
	v_pk_mul_f32 v[210:211], v[210:211], v[180:181] op_sel:[0,1] op_sel_hi:[1,1]
	v_pk_fma_f32 v[208:209], v[208:209], v[166:167], v[170:171]
	v_pk_fma_f32 v[210:211], v[210:211], v[168:169], v[172:173]
	v_pk_fma_f32 v[198:199], v[208:209], s[16:17], v[198:199] op_sel_hi:[1,0,1]
	v_pk_fma_f32 v[200:201], v[210:211], s[16:17], v[200:201] op_sel_hi:[1,0,1]
	global_store_dwordx4 v140, v[198:201], s[88:89] offset:512
	global_load_dwordx2 v[178:179], v141, s[76:77] offset:1408
	global_load_dwordx2 v[180:181], v141, s[76:77] offset:1472
	ds_write_b128 v144, v[26:29]
	ds_write_b128 v144, v[22:25] offset:1024
	ds_read_b128 v[194:197], v145
	ds_read_b128 v[198:201], v145 offset:512
	s_waitcnt lgkmcnt(4)
	s_waitcnt vmcnt(8)
	v_pk_add_f32 v[212:213], v[212:213], v[174:175] op_sel_hi:[1,0] neg_lo:[0,1] neg_hi:[0,1]
	v_pk_add_f32 v[214:215], v[214:215], v[174:175] op_sel_hi:[1,0] neg_lo:[0,1] neg_hi:[0,1]
	v_pk_mul_f32 v[212:213], v[212:213], v[174:175] op_sel:[0,1] op_sel_hi:[1,1]
	v_pk_mul_f32 v[214:215], v[214:215], v[174:175] op_sel:[0,1] op_sel_hi:[1,1]
	v_pk_fma_f32 v[212:213], v[212:213], v[154:155], v[162:163]
	v_pk_fma_f32 v[214:215], v[214:215], v[156:157], v[164:165]
	v_pk_fma_f32 v[186:187], v[212:213], s[16:17], v[186:187] op_sel_hi:[1,0,1]
	v_pk_fma_f32 v[188:189], v[214:215], s[16:17], v[188:189] op_sel_hi:[1,0,1]
	global_store_dwordx4 v140, v[186:189], s[68:69]
	s_waitcnt vmcnt(8)
	v_pk_add_f32 v[216:217], v[216:217], v[176:177] op_sel_hi:[1,0] neg_lo:[0,1] neg_hi:[0,1]
	v_pk_add_f32 v[218:219], v[218:219], v[176:177] op_sel_hi:[1,0] neg_lo:[0,1] neg_hi:[0,1]
	v_pk_mul_f32 v[216:217], v[216:217], v[176:177] op_sel:[0,1] op_sel_hi:[1,1]
	v_pk_mul_f32 v[218:219], v[218:219], v[176:177] op_sel:[0,1] op_sel_hi:[1,1]
	v_pk_fma_f32 v[216:217], v[216:217], v[154:155], v[162:163]
	v_pk_fma_f32 v[218:219], v[218:219], v[156:157], v[164:165]
	v_pk_fma_f32 v[190:191], v[216:217], s[16:17], v[190:191] op_sel_hi:[1,0,1]
	v_pk_fma_f32 v[192:193], v[218:219], s[16:17], v[192:193] op_sel_hi:[1,0,1]
	global_store_dwordx4 v140, v[190:193], s[90:91]
	ds_write_b128 v144, v[12:15]
	ds_write_b128 v144, v[8:11] offset:1024
	ds_read_b128 v[186:189], v145
	ds_read_b128 v[190:193], v145 offset:512
	s_waitcnt lgkmcnt(4)
	s_waitcnt vmcnt(10)
	v_pk_add_f32 v[220:221], v[220:221], v[174:175] op_sel_hi:[1,0] neg_lo:[0,1] neg_hi:[0,1]
	v_pk_add_f32 v[222:223], v[222:223], v[174:175] op_sel_hi:[1,0] neg_lo:[0,1] neg_hi:[0,1]
	v_pk_mul_f32 v[220:221], v[220:221], v[174:175] op_sel:[0,1] op_sel_hi:[1,1]
	v_pk_mul_f32 v[222:223], v[222:223], v[174:175] op_sel:[0,1] op_sel_hi:[1,1]
	v_pk_fma_f32 v[220:221], v[220:221], v[166:167], v[170:171]
	v_pk_fma_f32 v[222:223], v[222:223], v[168:169], v[172:173]
	v_pk_fma_f32 v[194:195], v[220:221], s[16:17], v[194:195] op_sel_hi:[1,0,1]
	v_pk_fma_f32 v[196:197], v[222:223], s[16:17], v[196:197] op_sel_hi:[1,0,1]
	global_store_dwordx4 v140, v[194:197], s[68:69] offset:512
	s_waitcnt vmcnt(10)
; DI bf16x4 pack4(float a, float b, float c, float d) { u32x2v u; u.x = pk2(a, b); u.y = pk2(c, d); return __builtin_bit_cast(bf16x4, u); }
; DI void ln_rows2(const float* s0, const float* s1, const float* g, const float* b, float* d0, bf16_t* db0, float* d1, bf16_t* db1, int lane) {
;     ...
;   for (int i = 0; i < 4; ++i) {
;     const float4 gg = reinterpret_cast<const float4*>(g)[lane + 64 * i], bb = reinterpret_cast<const float4*>(b)[lane + 64 * i];
;     float4 o;
;     o.x = (v0[i].x - mu0) * r0 * gg.x + bb.x; o.y = (v0[i].y - mu0) * r0 * gg.y + bb.y; o.z = (v0[i].z - mu0) * r0 * gg.z + bb.z; o.w = (v0[i].w - mu0) * r0 * gg.w + bb.w;
;     reinterpret_cast<float4*>(d0)[lane + 64 * i] = o; st4(db0 + 4 * (lane + 64 * i), pack4(o.x, o.y, o.z, o.w));
;   DI void operator()(const f32x4 (&acc)[2][2][4][2], const pg8::Unit& u, int wr, int wc, int fr, int fq) const {
;     bf16_t* MERGED = (reinterpret_cast<bf16_t*>(p.ws + OFF_GA));
; #pragma unroll
;     for (int ai = 0; ai < 2; ++ai)
; #pragma unroll
;       for (int m = 0; m < 4; ++m) {
;         const int row = u.pm * 256 + 128 * ai + 64 * wr + 16 * m + fr;
; #pragma unroll
;         for (int bj = 0; bj < 2; ++bj)
; #pragma unroll
;           for (int n = 0; n < 2; ++n) {
;             const size_t idx = (size_t)row * 1024 + u.pn * 256 + 128 * bj + 32 * wc + 16 * n + 4 * fq;
;             const f32x4 a = acc[ai][bj][m][n];
;             if (MODE == 0) {
;               const unsigned g = *reinterpret_cast<const unsigned*>(reinterpret_cast<const unsigned char*>(p.ws + OFF_RB) + idx);
;               const float k = 1.f / 255.f;
;               st4(MERGED + idx, pack4((float)(g & 255u) * k * a[0], (float)((g >> 8) & 255u) * k * a[1], (float)((g >> 16) & 255u) * k * a[2], (float)(g >> 24) * k * a[3]));
;             } else {
;               f32x4 x = *reinterpret_cast<const f32x4*>(p.out + idx);
;               x = x * ALPHA + a;
;               *reinterpret_cast<f32x4*>(p.out + idx) = x;
;             }
;           }
;       }
;   }
	v_pk_add_f32 v[224:225], v[224:225], v[176:177] op_sel_hi:[1,0] neg_lo:[0,1] neg_hi:[0,1]
	v_pk_add_f32 v[226:227], v[226:227], v[176:177] op_sel_hi:[1,0] neg_lo:[0,1] neg_hi:[0,1]
	v_pk_mul_f32 v[224:225], v[224:225], v[176:177] op_sel:[0,1] op_sel_hi:[1,1]
	v_pk_mul_f32 v[226:227], v[226:227], v[176:177] op_sel:[0,1] op_sel_hi:[1,1]
	v_pk_fma_f32 v[224:225], v[224:225], v[166:167], v[170:171]
	v_pk_fma_f32 v[226:227], v[226:227], v[168:169], v[172:173]
	v_pk_fma_f32 v[198:199], v[224:225], s[16:17], v[198:199] op_sel_hi:[1,0,1]
	v_pk_fma_f32 v[200:201], v[226:227], s[16:17], v[200:201] op_sel_hi:[1,0,1]
	global_store_dwordx4 v140, v[198:201], s[90:91] offset:512
	ds_write_b128 v144, v[4:7]
	ds_write_b128 v144, v[0:3] offset:1024
	ds_read_b128 v[194:197], v145
	ds_read_b128 v[198:201], v145 offset:512
	s_waitcnt lgkmcnt(4)
	s_waitcnt vmcnt(5)
	v_pk_add_f32 v[228:229], v[228:229], v[178:179] op_sel_hi:[1,0] neg_lo:[0,1] neg_hi:[0,1]
	v_pk_add_f32 v[230:231], v[230:231], v[178:179] op_sel_hi:[1,0] neg_lo:[0,1] neg_hi:[0,1]
	v_pk_mul_f32 v[228:229], v[228:229], v[178:179] op_sel:[0,1] op_sel_hi:[1,1]
	v_pk_mul_f32 v[230:231], v[230:231], v[178:179] op_sel:[0,1] op_sel_hi:[1,1]
	v_pk_fma_f32 v[228:229], v[228:229], v[154:155], v[162:163]
	v_pk_fma_f32 v[230:231], v[230:231], v[156:157], v[164:165]
	v_pk_fma_f32 v[186:187], v[228:229], s[16:17], v[186:187] op_sel_hi:[1,0,1]
	v_pk_fma_f32 v[188:189], v[230:231], s[16:17], v[188:189] op_sel_hi:[1,0,1]
	global_store_dwordx4 v140, v[186:189], s[70:71]
	s_waitcnt vmcnt(5)
	v_pk_add_f32 v[232:233], v[232:233], v[180:181] op_sel_hi:[1,0] neg_lo:[0,1] neg_hi:[0,1]
	v_pk_add_f32 v[234:235], v[234:235], v[180:181] op_sel_hi:[1,0] neg_lo:[0,1] neg_hi:[0,1]
	v_pk_mul_f32 v[232:233], v[232:233], v[180:181] op_sel:[0,1] op_sel_hi:[1,1]
	v_pk_mul_f32 v[234:235], v[234:235], v[180:181] op_sel:[0,1] op_sel_hi:[1,1]
	v_pk_fma_f32 v[232:233], v[232:233], v[154:155], v[162:163]
	v_pk_fma_f32 v[234:235], v[234:235], v[156:157], v[164:165]
	v_pk_fma_f32 v[190:191], v[232:233], s[16:17], v[190:191] op_sel_hi:[1,0,1]
	v_pk_fma_f32 v[192:193], v[234:235], s[16:17], v[192:193] op_sel_hi:[1,0,1]
	global_store_dwordx4 v140, v[190:193], s[92:93]
	s_waitcnt lgkmcnt(0)
	s_waitcnt vmcnt(7)
	v_pk_add_f32 v[236:237], v[236:237], v[178:179] op_sel_hi:[1,0] neg_lo:[0,1] neg_hi:[0,1]
	v_pk_add_f32 v[238:239], v[238:239], v[178:179] op_sel_hi:[1,0] neg_lo:[0,1] neg_hi:[0,1]
	v_pk_mul_f32 v[236:237], v[236:237], v[178:179] op_sel:[0,1] op_sel_hi:[1,1]
	v_pk_mul_f32 v[238:239], v[238:239], v[178:179] op_sel:[0,1] op_sel_hi:[1,1]
	v_pk_fma_f32 v[236:237], v[236:237], v[166:167], v[170:171]
	v_pk_fma_f32 v[238:239], v[238:239], v[168:169], v[172:173]
	v_pk_fma_f32 v[194:195], v[236:237], s[16:17], v[194:195] op_sel_hi:[1,0,1]
	v_pk_fma_f32 v[196:197], v[238:239], s[16:17], v[196:197] op_sel_hi:[1,0,1]
	global_store_dwordx4 v140, v[194:197], s[70:71] offset:512
	s_waitcnt vmcnt(7)
	v_pk_add_f32 v[240:241], v[240:241], v[180:181] op_sel_hi:[1,0] neg_lo:[0,1] neg_hi:[0,1]
	v_pk_add_f32 v[242:243], v[242:243], v[180:181] op_sel_hi:[1,0] neg_lo:[0,1] neg_hi:[0,1]
	v_pk_mul_f32 v[240:241], v[240:241], v[180:181] op_sel:[0,1] op_sel_hi:[1,1]
	v_pk_mul_f32 v[242:243], v[242:243], v[180:181] op_sel:[0,1] op_sel_hi:[1,1]
	v_pk_fma_f32 v[240:241], v[240:241], v[166:167], v[170:171]
	v_pk_fma_f32 v[242:243], v[242:243], v[168:169], v[172:173]
	v_pk_fma_f32 v[198:199], v[240:241], s[16:17], v[198:199] op_sel_hi:[1,0,1]
	v_pk_fma_f32 v[200:201], v[242:243], s[16:17], v[200:201] op_sel_hi:[1,0,1]
	global_store_dwordx4 v140, v[198:201], s[92:93] offset:512
	s_branch .Llz_join
